# back-edge rotation in the four GEMM K-loops: counter/exit-test/next-tile address SALU moved in front of the loop-back barrier
# baseline (speedup 1.0000x reference)
; #define PG8_STAGE(bufoff, gbase, voff) do { _Pragma("unroll") for (int _i = 0; _i < 2; ++_i) \
;         __builtin_amdgcn_global_load_lds((const unsigned*)((const char*)(gbase) + (voff)[_i]), (LAS unsigned*)(lds + (bufoff) + ldsw + _i * 8192), 16, 0, 0); } while (0)
; #define PG8_LDA(dst, b, h) do { _Pragma("unroll") for (int m = 0; m < 4; ++m) _Pragma("unroll") for (int k = 0; k < 2; ++k) dst[m][k] = *(const LAS bf16x8*)(lds + PG8_SA(b, h) + aoff + m * 2048 + k * 1024); } while (0)
; #define PG8_LDB(dst, b, h) do { _Pragma("unroll") for (int n = 0; n < 2; ++n) _Pragma("unroll") for (int k = 0; k < 2; ++k) dst[n][k] = *(const LAS bf16x8*)(lds + PG8_SB(b, h) + boff + n * 2048 + k * 1024); } while (0)
; #define PG8_MMA(ai, bj, At, Bt) do { __builtin_amdgcn_s_setprio(1); _Pragma("unroll") for (int m = 0; m < 4; ++m) _Pragma("unroll") for (int n = 0; n < 2; ++n) _Pragma("unroll") for (int k = 0; k < 2; ++k) \
;         acc[ai][bj][m][n] = __builtin_amdgcn_mfma_f32_16x16x32_bf16(Bt[n][k], At[m][k], acc[ai][bj][m][n], 0, 0, 0); __builtin_amdgcn_s_setprio(0); } while (0)
; #define PG8_WAIT_V(n) asm volatile("s_waitcnt vmcnt(" #n ")" ::: "memory")
; #define PG8_WAIT_L(n) asm volatile("s_waitcnt lgkmcnt(" #n ")" ::: "memory")
; #define PG8_BAR __builtin_amdgcn_s_barrier()
; #define PG8_SCHED __builtin_amdgcn_sched_barrier(0)
; template <class Epi, bool ALIGN_EPI = true>
; __device__ __forceinline__ void gemm_phase(LAS unsigned char* lds, const Gemm g, const StaticOrder& S, const Epi& E) {
;     ...
;         for (int t = 0; t < nt; t += 2) {
;             const bool last = (t == nt - 2);
;             const char* a1 = cA + (size_t)(t + 1) * kstep;
;             const char* a2 = last ? nA : cA + (size_t)(t + 2) * kstep; const char* b2 = last ? nB : cB + (size_t)(t + 2) * kstep;
;             const char* a3 = a2 + kstep; const char* b3 = b2 + kstep;
;             PG8_LDB(B0, 0, 0); PG8_LDB(B1, 0, 1); PG8_SCHED; PG8_LDA(At, 0, 0); PG8_STAGE(PG8_SA(1, 1), a1 + hsA, voffA);
;             PG8_WAIT_V(8); PG8_WAIT_L(0); PG8_BAR; PG8_MMA(0, 0, At, B0); PG8_MMA(0, 1, At, B1); PG8_BAR; PG8_SCHED;
;             PG8_LDA(At, 0, 1); PG8_STAGE(PG8_SB(0, 0), b2, voffB); PG8_STAGE(PG8_SB(0, 1), b2 + hsB, voffB); PG8_STAGE(PG8_SA(0, 0), a2, voffA);
;             PG8_WAIT_V(8); PG8_WAIT_L(0); PG8_BAR; PG8_MMA(1, 0, At, B0); PG8_MMA(1, 1, At, B1); PG8_BAR; PG8_SCHED;
.LBB0_228:
	s_mov_b32 s84, 0
	s_mov_b64 vcc, 0x100
	v_mov_b64_e32 v[146:147], v[144:145]
	v_mov_b64_e32 v[148:149], v[142:143]
	s_mov_b64 s[86:87], 0x100
	s_add_i32 s11, s84, 2
	s_add_u32 s80, s6, vcc_lo
	s_addc_u32 s81, s7, vcc_hi
	s_add_u32 s97, s82, vcc_lo
	s_addc_u32 s22, s83, vcc_hi
	s_cmp_eq_u32 s72, s84
	s_cselect_b32 s85, s9, s81
	s_cselect_b32 s84, s8, s80
	s_cselect_b32 s81, s89, s22
	s_cselect_b32 s80, s88, s97
	s_add_i32 s22, 0, 0x14000
	v_add_u32_e32 v164, s91, v150
	v_add_u32_e32 v168, s22, v150
.LBB0_229:
	ds_read_b128 v[152:155], v164
	ds_read_b128 v[156:159], v164 offset:1024
	ds_read_b128 v[160:163], v164 offset:2048
	ds_read_b128 v[164:167], v164 offset:3072
	ds_read_b128 v[176:179], v168
	ds_read_b128 v[180:183], v168 offset:1024
	ds_read_b128 v[184:187], v168 offset:2048
	ds_read_b128 v[188:191], v168 offset:3072
	v_lshl_add_u64 v[168:169], s[6:7], 0, v[148:149]
	s_add_i32 m0, s25, 0xc000
	ds_read_b128 v[192:195], v151
	ds_read_b128 v[196:199], v151 offset:1024
	ds_read_b128 v[200:203], v151 offset:2048
	ds_read_b128 v[222:225], v151 offset:3072
	ds_read_b128 v[226:229], v151 offset:4096
	ds_read_b128 v[230:233], v151 offset:5120
	ds_read_b128 v[234:237], v151 offset:6144
	ds_read_b128 v[238:241], v151 offset:7168
	global_load_lds_dwordx4 v[168:169], off
	v_lshl_add_u64 v[168:169], s[6:7], 0, v[146:147]
	s_add_i32 m0, s25, 0xe000
	s_nop 0
	global_load_lds_dwordx4 v[168:169], off
	s_waitcnt vmcnt(8)
	s_waitcnt lgkmcnt(0)
	s_barrier
	s_setprio 1
	s_waitcnt lgkmcnt(0)
	v_mfma_f32_16x16x32_bf16 v[134:137], v[152:155], v[192:195], v[134:137]
	v_mfma_f32_16x16x32_bf16 v[130:133], v[160:163], v[192:195], v[130:133]
	v_mfma_f32_16x16x32_bf16 v[118:121], v[152:155], v[200:203], v[118:121]
	v_mfma_f32_16x16x32_bf16 v[114:117], v[160:163], v[200:203], v[114:117]
	v_mfma_f32_16x16x32_bf16 v[102:105], v[152:155], v[226:229], v[102:105]
	v_mfma_f32_16x16x32_bf16 v[98:101], v[160:163], v[226:229], v[98:101]
	v_mfma_f32_16x16x32_bf16 v[86:89], v[152:155], v[234:237], v[86:89]
	v_mfma_f32_16x16x32_bf16 v[82:85], v[160:163], v[234:237], v[82:85]
	v_mfma_f32_16x16x32_bf16 v[134:137], v[156:159], v[196:199], v[134:137]
	v_mfma_f32_16x16x32_bf16 v[130:133], v[164:167], v[196:199], v[130:133]
	v_mfma_f32_16x16x32_bf16 v[118:121], v[156:159], v[222:225], v[118:121]
	v_mfma_f32_16x16x32_bf16 v[114:117], v[164:167], v[222:225], v[114:117]
	v_mfma_f32_16x16x32_bf16 v[102:105], v[156:159], v[230:233], v[102:105]
	v_mfma_f32_16x16x32_bf16 v[98:101], v[164:167], v[230:233], v[98:101]
	v_mfma_f32_16x16x32_bf16 v[86:89], v[156:159], v[238:241], v[86:89]
	v_mfma_f32_16x16x32_bf16 v[82:85], v[164:167], v[238:241], v[82:85]
	s_setprio 0
	s_setprio 1
	v_mfma_f32_16x16x32_bf16 v[126:129], v[176:179], v[192:195], v[126:129]
	v_mfma_f32_16x16x32_bf16 v[122:125], v[184:187], v[192:195], v[122:125]
	v_mfma_f32_16x16x32_bf16 v[110:113], v[176:179], v[200:203], v[110:113]
	v_mfma_f32_16x16x32_bf16 v[106:109], v[184:187], v[200:203], v[106:109]
	v_mfma_f32_16x16x32_bf16 v[94:97], v[176:179], v[226:229], v[94:97]
	v_mfma_f32_16x16x32_bf16 v[90:93], v[184:187], v[226:229], v[90:93]
	v_mfma_f32_16x16x32_bf16 v[78:81], v[176:179], v[234:237], v[78:81]
	v_mfma_f32_16x16x32_bf16 v[74:77], v[184:187], v[234:237], v[74:77]
	v_mfma_f32_16x16x32_bf16 v[126:129], v[180:183], v[196:199], v[126:129]
	v_mfma_f32_16x16x32_bf16 v[122:125], v[188:191], v[196:199], v[122:125]
	v_mfma_f32_16x16x32_bf16 v[110:113], v[180:183], v[222:225], v[110:113]
	v_mfma_f32_16x16x32_bf16 v[106:109], v[188:191], v[222:225], v[106:109]
	v_mfma_f32_16x16x32_bf16 v[94:97], v[180:183], v[230:233], v[94:97]
	v_mfma_f32_16x16x32_bf16 v[90:93], v[188:191], v[230:233], v[90:93]
	v_mfma_f32_16x16x32_bf16 v[78:81], v[180:183], v[238:241], v[78:81]
	v_mfma_f32_16x16x32_bf16 v[74:77], v[188:191], v[238:241], v[74:77]
	s_setprio 0
	s_barrier
	s_add_i32 s97, s91, s3
	v_lshl_add_u64 v[168:169], s[80:81], 0, v[2:3]
	s_mov_b32 m0, s97
	ds_read_b128 v[192:195], v151 offset:16384
	ds_read_b128 v[196:199], v151 offset:17408
	ds_read_b128 v[200:203], v151 offset:18432
	ds_read_b128 v[222:225], v151 offset:19456
	ds_read_b128 v[226:229], v151 offset:20480
	ds_read_b128 v[230:233], v151 offset:21504
	ds_read_b128 v[234:237], v151 offset:22528
	ds_read_b128 v[238:241], v151 offset:23552
	global_load_lds_dwordx4 v[168:169], off
	s_add_i32 m0, s97, 0x2000
	v_lshl_add_u64 v[172:173], s[80:81], 0, v[4:5]
	s_add_u32 s80, s80, s96
	s_addc_u32 s81, s81, 0
	s_add_i32 s22, s22, s3
	global_load_lds_dwordx4 v[172:173], off
	v_lshl_add_u64 v[244:245], s[80:81], 0, v[2:3]
	s_mov_b32 m0, s22
	v_lshl_add_u64 v[246:247], s[80:81], 0, v[4:5]
	global_load_lds_dwordx4 v[244:245], off
	s_add_i32 m0, s22, 0x2000
	v_lshl_add_u64 v[248:249], s[84:85], 0, v[140:141]
	global_load_lds_dwordx4 v[246:247], off
	s_mov_b32 m0, s25
	v_lshl_add_u64 v[250:251], s[84:85], 0, v[138:139]
	global_load_lds_dwordx4 v[248:249], off
	s_mov_b32 m0, s26
	s_nop 0
	global_load_lds_dwordx4 v[250:251], off
	s_waitcnt vmcnt(8)
	s_waitcnt lgkmcnt(0)
	s_barrier
; #define PG8_STAGE(bufoff, gbase, voff) do { _Pragma("unroll") for (int _i = 0; _i < 2; ++_i) \
;         __builtin_amdgcn_global_load_lds((const unsigned*)((const char*)(gbase) + (voff)[_i]), (LAS unsigned*)(lds + (bufoff) + ldsw + _i * 8192), 16, 0, 0); } while (0)
; #define PG8_LDA(dst, b, h) do { _Pragma("unroll") for (int m = 0; m < 4; ++m) _Pragma("unroll") for (int k = 0; k < 2; ++k) dst[m][k] = *(const LAS bf16x8*)(lds + PG8_SA(b, h) + aoff + m * 2048 + k * 1024); } while (0)
; #define PG8_LDB(dst, b, h) do { _Pragma("unroll") for (int n = 0; n < 2; ++n) _Pragma("unroll") for (int k = 0; k < 2; ++k) dst[n][k] = *(const LAS bf16x8*)(lds + PG8_SB(b, h) + boff + n * 2048 + k * 1024); } while (0)
; #define PG8_MMA(ai, bj, At, Bt) do { __builtin_amdgcn_s_setprio(1); _Pragma("unroll") for (int m = 0; m < 4; ++m) _Pragma("unroll") for (int n = 0; n < 2; ++n) _Pragma("unroll") for (int k = 0; k < 2; ++k) \
;         acc[ai][bj][m][n] = __builtin_amdgcn_mfma_f32_16x16x32_bf16(Bt[n][k], At[m][k], acc[ai][bj][m][n], 0, 0, 0); __builtin_amdgcn_s_setprio(0); } while (0)
; #define PG8_WAIT_V(n) asm volatile("s_waitcnt vmcnt(" #n ")" ::: "memory")
; #define PG8_WAIT_L(n) asm volatile("s_waitcnt lgkmcnt(" #n ")" ::: "memory")
; #define PG8_BAR __builtin_amdgcn_s_barrier()
; #define PG8_SCHED __builtin_amdgcn_sched_barrier(0)
; template <class Epi, bool ALIGN_EPI = true>
; __device__ __forceinline__ void gemm_phase(LAS unsigned char* lds, const Gemm g, const StaticOrder& S, const Epi& E) {
;     ...
;             PG8_WAIT_V(8); PG8_WAIT_L(0); PG8_BAR; PG8_MMA(1, 0, At, B0); PG8_MMA(1, 1, At, B1); PG8_BAR; PG8_SCHED;
;             PG8_LDB(B0, 1, 0); PG8_LDB(B1, 1, 1); PG8_SCHED; PG8_LDA(At, 1, 0); PG8_STAGE(PG8_SA(0, 1), a2 + hsA, voffA);
;             PG8_WAIT_V(8); PG8_WAIT_L(0); PG8_BAR; PG8_MMA(0, 0, At, B0); PG8_MMA(0, 1, At, B1); PG8_BAR; PG8_SCHED;
	s_setprio 1
	s_waitcnt lgkmcnt(0)
	v_mfma_f32_16x16x32_bf16 v[70:73], v[152:155], v[192:195], v[70:73]
	v_mfma_f32_16x16x32_bf16 v[66:69], v[160:163], v[192:195], v[66:69]
	v_mfma_f32_16x16x32_bf16 v[54:57], v[152:155], v[200:203], v[54:57]
	v_mfma_f32_16x16x32_bf16 v[50:53], v[160:163], v[200:203], v[50:53]
	v_mfma_f32_16x16x32_bf16 v[38:41], v[152:155], v[226:229], v[38:41]
	v_mfma_f32_16x16x32_bf16 v[34:37], v[160:163], v[226:229], v[34:37]
	v_mfma_f32_16x16x32_bf16 v[22:25], v[152:155], v[234:237], v[22:25]
	v_mfma_f32_16x16x32_bf16 v[18:21], v[160:163], v[234:237], v[18:21]
	v_mfma_f32_16x16x32_bf16 v[70:73], v[156:159], v[196:199], v[70:73]
	v_mfma_f32_16x16x32_bf16 v[66:69], v[164:167], v[196:199], v[66:69]
	v_mfma_f32_16x16x32_bf16 v[54:57], v[156:159], v[222:225], v[54:57]
	v_mfma_f32_16x16x32_bf16 v[50:53], v[164:167], v[222:225], v[50:53]
	v_mfma_f32_16x16x32_bf16 v[38:41], v[156:159], v[230:233], v[38:41]
	v_mfma_f32_16x16x32_bf16 v[34:37], v[164:167], v[230:233], v[34:37]
	v_mfma_f32_16x16x32_bf16 v[22:25], v[156:159], v[238:241], v[22:25]
	v_mfma_f32_16x16x32_bf16 v[18:21], v[164:167], v[238:241], v[18:21]
	s_setprio 0
	s_setprio 1
	v_mfma_f32_16x16x32_bf16 v[62:65], v[176:179], v[192:195], v[62:65]
	v_mfma_f32_16x16x32_bf16 v[58:61], v[184:187], v[192:195], v[58:61]
	v_mfma_f32_16x16x32_bf16 v[46:49], v[176:179], v[200:203], v[46:49]
	v_mfma_f32_16x16x32_bf16 v[42:45], v[184:187], v[200:203], v[42:45]
	v_mfma_f32_16x16x32_bf16 v[30:33], v[176:179], v[226:229], v[30:33]
	v_mfma_f32_16x16x32_bf16 v[26:29], v[184:187], v[226:229], v[26:29]
	v_mfma_f32_16x16x32_bf16 v[14:17], v[176:179], v[234:237], v[14:17]
	v_mfma_f32_16x16x32_bf16 v[10:13], v[184:187], v[234:237], v[10:13]
	v_mfma_f32_16x16x32_bf16 v[62:65], v[180:183], v[196:199], v[62:65]
	v_mfma_f32_16x16x32_bf16 v[58:61], v[188:191], v[196:199], v[58:61]
	v_mfma_f32_16x16x32_bf16 v[46:49], v[180:183], v[222:225], v[46:49]
	v_mfma_f32_16x16x32_bf16 v[42:45], v[188:191], v[222:225], v[42:45]
	v_mfma_f32_16x16x32_bf16 v[30:33], v[180:183], v[230:233], v[30:33]
	v_mfma_f32_16x16x32_bf16 v[26:29], v[188:191], v[230:233], v[26:29]
	v_mfma_f32_16x16x32_bf16 v[14:17], v[180:183], v[238:241], v[14:17]
	v_mfma_f32_16x16x32_bf16 v[10:13], v[188:191], v[238:241], v[10:13]
	s_setprio 0
	s_barrier
	s_add_i32 s22, 0, 0x18000
	s_add_i32 s97, 0, 0x1c000
	v_add_u32_e32 v164, s22, v150
	v_add_u32_e32 v188, s97, v150
	ds_read_b128 v[152:155], v164
	ds_read_b128 v[156:159], v164 offset:1024
	ds_read_b128 v[160:163], v164 offset:2048
	ds_read_b128 v[164:167], v164 offset:3072
	ds_read_b128 v[176:179], v188
	ds_read_b128 v[180:183], v188 offset:1024
	ds_read_b128 v[184:187], v188 offset:2048
	ds_read_b128 v[188:191], v188 offset:3072
	s_add_u32 s80, s84, s14
	s_addc_u32 s81, s85, 0
	s_mov_b32 m0, s36
	v_lshl_add_u64 v[204:205], s[80:81], 0, v[140:141]
	ds_read_b128 v[192:195], v151 offset:32768
	ds_read_b128 v[196:199], v151 offset:33792
	ds_read_b128 v[200:203], v151 offset:34816
	ds_read_b128 v[222:225], v151 offset:35840
	ds_read_b128 v[226:229], v151 offset:36864
	ds_read_b128 v[230:233], v151 offset:37888
	ds_read_b128 v[234:237], v151 offset:38912
	ds_read_b128 v[238:241], v151 offset:39936
	global_load_lds_dwordx4 v[204:205], off
	v_lshl_add_u64 v[204:205], s[80:81], 0, v[138:139]
	s_mov_b32 m0, s69
	s_nop 0
	global_load_lds_dwordx4 v[204:205], off
	s_waitcnt vmcnt(8)
	s_waitcnt lgkmcnt(0)
	s_barrier
	s_setprio 1
	s_waitcnt lgkmcnt(0)
	v_mfma_f32_16x16x32_bf16 v[134:137], v[152:155], v[192:195], v[134:137]
	v_mfma_f32_16x16x32_bf16 v[130:133], v[160:163], v[192:195], v[130:133]
	v_mfma_f32_16x16x32_bf16 v[118:121], v[152:155], v[200:203], v[118:121]
	v_mfma_f32_16x16x32_bf16 v[114:117], v[160:163], v[200:203], v[114:117]
	v_mfma_f32_16x16x32_bf16 v[102:105], v[152:155], v[226:229], v[102:105]
	v_mfma_f32_16x16x32_bf16 v[98:101], v[160:163], v[226:229], v[98:101]
	v_mfma_f32_16x16x32_bf16 v[86:89], v[152:155], v[234:237], v[86:89]
	v_mfma_f32_16x16x32_bf16 v[82:85], v[160:163], v[234:237], v[82:85]
	v_mfma_f32_16x16x32_bf16 v[134:137], v[156:159], v[196:199], v[134:137]
	v_mfma_f32_16x16x32_bf16 v[130:133], v[164:167], v[196:199], v[130:133]
	v_mfma_f32_16x16x32_bf16 v[118:121], v[156:159], v[222:225], v[118:121]
	v_mfma_f32_16x16x32_bf16 v[114:117], v[164:167], v[222:225], v[114:117]
	v_mfma_f32_16x16x32_bf16 v[102:105], v[156:159], v[230:233], v[102:105]
	v_mfma_f32_16x16x32_bf16 v[98:101], v[164:167], v[230:233], v[98:101]
	v_mfma_f32_16x16x32_bf16 v[86:89], v[156:159], v[238:241], v[86:89]
	v_mfma_f32_16x16x32_bf16 v[82:85], v[164:167], v[238:241], v[82:85]
	s_setprio 0
	s_setprio 1
	v_mfma_f32_16x16x32_bf16 v[126:129], v[176:179], v[192:195], v[126:129]
	v_mfma_f32_16x16x32_bf16 v[122:125], v[184:187], v[192:195], v[122:125]
	v_mfma_f32_16x16x32_bf16 v[110:113], v[176:179], v[200:203], v[110:113]
	v_mfma_f32_16x16x32_bf16 v[106:109], v[184:187], v[200:203], v[106:109]
	v_mfma_f32_16x16x32_bf16 v[94:97], v[176:179], v[226:229], v[94:97]
	v_mfma_f32_16x16x32_bf16 v[90:93], v[184:187], v[226:229], v[90:93]
	v_mfma_f32_16x16x32_bf16 v[78:81], v[176:179], v[234:237], v[78:81]
	v_mfma_f32_16x16x32_bf16 v[74:77], v[184:187], v[234:237], v[74:77]
	v_mfma_f32_16x16x32_bf16 v[126:129], v[180:183], v[196:199], v[126:129]
	v_mfma_f32_16x16x32_bf16 v[122:125], v[188:191], v[196:199], v[122:125]
	v_mfma_f32_16x16x32_bf16 v[110:113], v[180:183], v[222:225], v[110:113]
	v_mfma_f32_16x16x32_bf16 v[106:109], v[188:191], v[222:225], v[106:109]
	v_mfma_f32_16x16x32_bf16 v[94:97], v[180:183], v[230:233], v[94:97]
	v_mfma_f32_16x16x32_bf16 v[90:93], v[188:191], v[230:233], v[90:93]
	v_mfma_f32_16x16x32_bf16 v[78:81], v[180:183], v[238:241], v[78:81]
	v_mfma_f32_16x16x32_bf16 v[74:77], v[188:191], v[238:241], v[74:77]
	s_setprio 0
	s_barrier
; #define PG8_STAGE(bufoff, gbase, voff) do { _Pragma("unroll") for (int _i = 0; _i < 2; ++_i) \
;         __builtin_amdgcn_global_load_lds((const unsigned*)((const char*)(gbase) + (voff)[_i]), (LAS unsigned*)(lds + (bufoff) + ldsw + _i * 8192), 16, 0, 0); } while (0)
; #define PG8_LDA(dst, b, h) do { _Pragma("unroll") for (int m = 0; m < 4; ++m) _Pragma("unroll") for (int k = 0; k < 2; ++k) dst[m][k] = *(const LAS bf16x8*)(lds + PG8_SA(b, h) + aoff + m * 2048 + k * 1024); } while (0)
; #define PG8_MMA(ai, bj, At, Bt) do { __builtin_amdgcn_s_setprio(1); _Pragma("unroll") for (int m = 0; m < 4; ++m) _Pragma("unroll") for (int n = 0; n < 2; ++n) _Pragma("unroll") for (int k = 0; k < 2; ++k) \
;         acc[ai][bj][m][n] = __builtin_amdgcn_mfma_f32_16x16x32_bf16(Bt[n][k], At[m][k], acc[ai][bj][m][n], 0, 0, 0); __builtin_amdgcn_s_setprio(0); } while (0)
; #define PG8_WAIT_V(n) asm volatile("s_waitcnt vmcnt(" #n ")" ::: "memory")
; #define PG8_WAIT_L(n) asm volatile("s_waitcnt lgkmcnt(" #n ")" ::: "memory")
; #define PG8_BAR __builtin_amdgcn_s_barrier()
; #define PG8_SCHED __builtin_amdgcn_sched_barrier(0)
; template <class Epi, bool ALIGN_EPI = true>
; __device__ __forceinline__ void gemm_phase(LAS unsigned char* lds, const Gemm g, const StaticOrder& S, const Epi& E) {
;     ...
;         for (int t = 0; t < nt; t += 2) {
;             const bool last = (t == nt - 2);
;             const char* a1 = cA + (size_t)(t + 1) * kstep;
;             const char* a2 = last ? nA : cA + (size_t)(t + 2) * kstep; const char* b2 = last ? nB : cB + (size_t)(t + 2) * kstep;
;             const char* a3 = a2 + kstep; const char* b3 = b2 + kstep;
;     ...
;             PG8_WAIT_V(8); PG8_WAIT_L(0); PG8_BAR; PG8_MMA(0, 0, At, B0); PG8_MMA(0, 1, At, B1); PG8_BAR; PG8_SCHED;
;             PG8_LDA(At, 1, 1); PG8_STAGE(PG8_SB(1, 0), b3, voffB); PG8_STAGE(PG8_SB(1, 1), b3 + hsB, voffB); PG8_STAGE(PG8_SA(1, 0), a3, voffA);
;             PG8_WAIT_V(8); PG8_WAIT_L(0); PG8_BAR; PG8_MMA(1, 0, At, B0); PG8_MMA(1, 1, At, B1); PG8_BAR; PG8_SCHED;
;         }
	s_add_i32 s22, s22, s3
	v_lshl_add_u64 v[168:169], v[168:169], 0, s[70:71]
	s_mov_b32 m0, s22
	ds_read_b128 v[192:195], v151 offset:49152
	ds_read_b128 v[196:199], v151 offset:50176
	ds_read_b128 v[200:203], v151 offset:51200
	ds_read_b128 v[222:225], v151 offset:52224
	ds_read_b128 v[226:229], v151 offset:53248
	ds_read_b128 v[230:233], v151 offset:54272
	ds_read_b128 v[234:237], v151 offset:55296
	ds_read_b128 v[238:241], v151 offset:56320
	global_load_lds_dwordx4 v[168:169], off
	v_lshl_add_u64 v[168:169], v[172:173], 0, s[70:71]
	s_add_i32 m0, s22, 0x2000
	s_add_i32 s22, s97, s3
	global_load_lds_dwordx4 v[168:169], off
	v_lshl_add_u64 v[168:169], v[244:245], 0, s[70:71]
	s_mov_b32 m0, s22
	s_nop 0
	global_load_lds_dwordx4 v[168:169], off
	v_lshl_add_u64 v[168:169], v[246:247], 0, s[70:71]
	s_add_i32 m0, s22, 0x2000
	s_nop 0
	global_load_lds_dwordx4 v[168:169], off
	v_lshl_add_u64 v[168:169], v[248:249], 0, s[70:71]
	s_mov_b32 m0, s73
	s_nop 0
	global_load_lds_dwordx4 v[168:169], off
	v_lshl_add_u64 v[168:169], v[250:251], 0, s[70:71]
	s_mov_b32 m0, s74
	s_nop 0
	global_load_lds_dwordx4 v[168:169], off
	s_waitcnt vmcnt(8)
	s_waitcnt lgkmcnt(0)
	s_barrier
	s_setprio 1
	s_waitcnt lgkmcnt(0)
	v_mfma_f32_16x16x32_bf16 v[70:73], v[152:155], v[192:195], v[70:73]
	v_mfma_f32_16x16x32_bf16 v[66:69], v[160:163], v[192:195], v[66:69]
	v_mfma_f32_16x16x32_bf16 v[54:57], v[152:155], v[200:203], v[54:57]
	v_mfma_f32_16x16x32_bf16 v[50:53], v[160:163], v[200:203], v[50:53]
	v_mfma_f32_16x16x32_bf16 v[38:41], v[152:155], v[226:229], v[38:41]
	v_mfma_f32_16x16x32_bf16 v[34:37], v[160:163], v[226:229], v[34:37]
	v_mfma_f32_16x16x32_bf16 v[22:25], v[152:155], v[234:237], v[22:25]
	v_mfma_f32_16x16x32_bf16 v[18:21], v[160:163], v[234:237], v[18:21]
	v_mfma_f32_16x16x32_bf16 v[70:73], v[156:159], v[196:199], v[70:73]
	v_mfma_f32_16x16x32_bf16 v[66:69], v[164:167], v[196:199], v[66:69]
	v_mfma_f32_16x16x32_bf16 v[54:57], v[156:159], v[222:225], v[54:57]
	v_mfma_f32_16x16x32_bf16 v[50:53], v[164:167], v[222:225], v[50:53]
	v_mfma_f32_16x16x32_bf16 v[38:41], v[156:159], v[230:233], v[38:41]
	v_mfma_f32_16x16x32_bf16 v[34:37], v[164:167], v[230:233], v[34:37]
	v_mfma_f32_16x16x32_bf16 v[22:25], v[156:159], v[238:241], v[22:25]
	v_mfma_f32_16x16x32_bf16 v[18:21], v[164:167], v[238:241], v[18:21]
	s_setprio 0
	s_setprio 1
	v_mfma_f32_16x16x32_bf16 v[62:65], v[176:179], v[192:195], v[62:65]
	v_mfma_f32_16x16x32_bf16 v[58:61], v[184:187], v[192:195], v[58:61]
	v_mfma_f32_16x16x32_bf16 v[46:49], v[176:179], v[200:203], v[46:49]
	v_mfma_f32_16x16x32_bf16 v[42:45], v[184:187], v[200:203], v[42:45]
	v_mfma_f32_16x16x32_bf16 v[30:33], v[176:179], v[226:229], v[30:33]
	v_mfma_f32_16x16x32_bf16 v[26:29], v[184:187], v[226:229], v[26:29]
	v_mfma_f32_16x16x32_bf16 v[14:17], v[176:179], v[234:237], v[14:17]
	v_mfma_f32_16x16x32_bf16 v[10:13], v[184:187], v[234:237], v[10:13]
	v_mfma_f32_16x16x32_bf16 v[62:65], v[180:183], v[196:199], v[62:65]
	v_mfma_f32_16x16x32_bf16 v[58:61], v[188:191], v[196:199], v[58:61]
	v_mfma_f32_16x16x32_bf16 v[46:49], v[180:183], v[222:225], v[46:49]
	v_mfma_f32_16x16x32_bf16 v[42:45], v[188:191], v[222:225], v[42:45]
	v_mfma_f32_16x16x32_bf16 v[30:33], v[180:183], v[230:233], v[30:33]
	v_mfma_f32_16x16x32_bf16 v[26:29], v[188:191], v[230:233], v[26:29]
	v_mfma_f32_16x16x32_bf16 v[14:17], v[180:183], v[238:241], v[14:17]
	v_mfma_f32_16x16x32_bf16 v[10:13], v[188:191], v[238:241], v[10:13]
	s_setprio 0
	s_add_u32 vcc_lo, vcc_lo, 0x100
	s_addc_u32 vcc_hi, vcc_hi, 0
	v_lshl_add_u64 v[148:149], v[148:149], 0, s[86:87]
	v_lshl_add_u64 v[146:147], v[146:147], 0, s[86:87]
	s_cmp_ge_u32 s11, s95
	s_mov_b32 s84, s11
	s_cbranch_scc1 .Lrot_exit_229
	s_add_i32 s11, s84, 2
	s_add_u32 s80, s6, vcc_lo
	s_addc_u32 s81, s7, vcc_hi
	s_add_u32 s97, s82, vcc_lo
	s_addc_u32 s22, s83, vcc_hi
	s_cmp_eq_u32 s72, s84
	s_cselect_b32 s85, s9, s81
	s_cselect_b32 s84, s8, s80
	s_cselect_b32 s81, s89, s22
	s_cselect_b32 s80, s88, s97
	s_add_i32 s22, 0, 0x14000
	v_add_u32_e32 v164, s91, v150
	v_add_u32_e32 v168, s22, v150
	s_barrier
	s_branch .LBB0_229
.Lrot_exit_229:
	s_barrier
	v_readlane_b32 s80, v255, 0
	v_readlane_b32 s81, v255, 1
	s_and_b64 vcc, exec, s[80:81]
	s_cbranch_vccz .LBB0_232
	s_barrier

; #define PG8_STAGE(bufoff, gbase, voff) do { _Pragma("unroll") for (int _i = 0; _i < 2; ++_i) \
;         __builtin_amdgcn_global_load_lds((const unsigned*)((const char*)(gbase) + (voff)[_i]), (LAS unsigned*)(lds + (bufoff) + ldsw + _i * 8192), 16, 0, 0); } while (0)
; #define PG8_LDA(dst, b, h) do { _Pragma("unroll") for (int m = 0; m < 4; ++m) _Pragma("unroll") for (int k = 0; k < 2; ++k) dst[m][k] = *(const LAS bf16x8*)(lds + PG8_SA(b, h) + aoff + m * 2048 + k * 1024); } while (0)
; #define PG8_LDB(dst, b, h) do { _Pragma("unroll") for (int n = 0; n < 2; ++n) _Pragma("unroll") for (int k = 0; k < 2; ++k) dst[n][k] = *(const LAS bf16x8*)(lds + PG8_SB(b, h) + boff + n * 2048 + k * 1024); } while (0)
; #define PG8_SCHED __builtin_amdgcn_sched_barrier(0)
; template <class Epi, bool ALIGN_EPI = true>
; __device__ __forceinline__ void gemm_phase(LAS unsigned char* lds, const Gemm g, const StaticOrder& S, const Epi& E) {
;     ...
;         const bool has_next = S.next(ui + 1, nxt);
;         const char* nA = has_next ? (const char*)g.A + (size_t)nxt.pm * tsA : cA; const char* nB = has_next ? (const char*)g.Bt + (size_t)nxt.pn * tsB : cB;
;         for (int t = 0; t < nt; t += 2) {
;             const bool last = (t == nt - 2);
;             const char* a1 = cA + (size_t)(t + 1) * kstep;
;             const char* a2 = last ? nA : cA + (size_t)(t + 2) * kstep; const char* b2 = last ? nB : cB + (size_t)(t + 2) * kstep;
;             const char* a3 = a2 + kstep; const char* b3 = b2 + kstep;
;             PG8_LDB(B0, 0, 0); PG8_LDB(B1, 0, 1); PG8_SCHED; PG8_LDA(At, 0, 0); PG8_STAGE(PG8_SA(1, 1), a1 + hsA, voffA);
;     ...
; #pragma unroll
;         for (int a = 0; a < 2; ++a)
; #pragma unroll
;             for (int b = 0; b < 2; ++b)
; #pragma unroll
;                 for (int m = 0; m < 4; ++m)
; #pragma unroll
;                     for (int n = 0; n < 2; ++n) acc[a][b][m][n] = (f32x4){0.f, 0.f, 0.f, 0.f};
;         cur = nxt; cA = nA; cB = nB; ++ui;
.LBB0_258:
	s_add_u32 s0, s8, 0x80
	s_addc_u32 s1, s9, 0
	s_add_u32 s8, s6, 0x100
	v_mov_b32_e32 v10, 0
	s_addc_u32 s9, s7, 0
	s_mov_b32 s6, 0
	v_mov_b32_e32 v11, v10
	v_mov_b32_e32 v12, v10
	v_mov_b32_e32 v13, v10
	v_mov_b32_e32 v14, v10
	v_mov_b32_e32 v15, v10
	v_mov_b32_e32 v16, v10
	v_mov_b32_e32 v17, v10
	v_mov_b32_e32 v26, v10
	v_mov_b32_e32 v27, v10
	v_mov_b32_e32 v28, v10
	v_mov_b32_e32 v29, v10
	v_mov_b32_e32 v30, v10
	v_mov_b32_e32 v31, v10
	v_mov_b32_e32 v32, v10
	v_mov_b32_e32 v33, v10
	v_mov_b32_e32 v42, v10
	v_mov_b32_e32 v43, v10
	v_mov_b32_e32 v44, v10
	v_mov_b32_e32 v45, v10
	v_mov_b32_e32 v46, v10
	v_mov_b32_e32 v47, v10
	v_mov_b32_e32 v48, v10
	v_mov_b32_e32 v49, v10
	v_mov_b32_e32 v62, v10
	v_mov_b32_e32 v63, v10
	v_mov_b32_e32 v64, v10
	v_mov_b32_e32 v65, v10
	v_mov_b32_e32 v78, v10
	v_mov_b32_e32 v79, v10
	v_mov_b32_e32 v80, v10
	v_mov_b32_e32 v81, v10
	v_mov_b32_e32 v18, v10
	v_mov_b32_e32 v19, v10
	v_mov_b32_e32 v20, v10
	v_mov_b32_e32 v21, v10
	v_mov_b32_e32 v22, v10
	v_mov_b32_e32 v23, v10
	v_mov_b32_e32 v24, v10
	v_mov_b32_e32 v25, v10
	v_mov_b32_e32 v34, v10
	v_mov_b32_e32 v35, v10
	v_mov_b32_e32 v36, v10
	v_mov_b32_e32 v37, v10
	v_mov_b32_e32 v38, v10
	v_mov_b32_e32 v39, v10
	v_mov_b32_e32 v40, v10
	v_mov_b32_e32 v41, v10
	v_mov_b32_e32 v50, v10
	v_mov_b32_e32 v51, v10
	v_mov_b32_e32 v52, v10
	v_mov_b32_e32 v53, v10
	v_mov_b32_e32 v54, v10
	v_mov_b32_e32 v55, v10
	v_mov_b32_e32 v56, v10
	v_mov_b32_e32 v57, v10
	v_mov_b32_e32 v82, v10
	v_mov_b32_e32 v83, v10
	v_mov_b32_e32 v84, v10
	v_mov_b32_e32 v85, v10
	v_mov_b32_e32 v86, v10
	v_mov_b32_e32 v87, v10
	v_mov_b32_e32 v88, v10
	v_mov_b32_e32 v89, v10
	v_mov_b32_e32 v106, v10
	v_mov_b32_e32 v107, v10
	v_mov_b32_e32 v108, v10
	v_mov_b32_e32 v109, v10
	v_mov_b32_e32 v110, v10
	v_mov_b32_e32 v111, v10
	v_mov_b32_e32 v112, v10
	v_mov_b32_e32 v113, v10
	v_mov_b32_e32 v122, v10
	v_mov_b32_e32 v123, v10
	v_mov_b32_e32 v124, v10
	v_mov_b32_e32 v125, v10
	v_mov_b32_e32 v126, v10
	v_mov_b32_e32 v127, v10
	v_mov_b32_e32 v128, v10
	v_mov_b32_e32 v129, v10
	v_mov_b32_e32 v138, v10
	v_mov_b32_e32 v139, v10
	v_mov_b32_e32 v140, v10
	v_mov_b32_e32 v141, v10
	v_mov_b32_e32 v142, v10
	v_mov_b32_e32 v143, v10
	v_mov_b32_e32 v144, v10
	v_mov_b32_e32 v145, v10
	v_mov_b32_e32 v154, v10
	v_mov_b32_e32 v155, v10
	v_mov_b32_e32 v156, v10
	v_mov_b32_e32 v157, v10
	v_mov_b32_e32 v158, v10
	v_mov_b32_e32 v159, v10
	v_mov_b32_e32 v160, v10
	v_mov_b32_e32 v161, v10
	v_mov_b32_e32 v114, v10
	v_mov_b32_e32 v115, v10
	v_mov_b32_e32 v116, v10
	v_mov_b32_e32 v117, v10
	v_mov_b32_e32 v118, v10
	v_mov_b32_e32 v119, v10
	v_mov_b32_e32 v120, v10
	v_mov_b32_e32 v121, v10
	v_mov_b32_e32 v130, v10
	v_mov_b32_e32 v131, v10
	v_mov_b32_e32 v132, v10
	v_mov_b32_e32 v133, v10
	v_mov_b32_e32 v134, v10
	v_mov_b32_e32 v135, v10
	v_mov_b32_e32 v136, v10
	v_mov_b32_e32 v137, v10
	v_mov_b32_e32 v146, v10
	v_mov_b32_e32 v147, v10
	v_mov_b32_e32 v148, v10
	v_mov_b32_e32 v149, v10
	v_mov_b32_e32 v150, v10
	v_mov_b32_e32 v151, v10
	v_mov_b32_e32 v152, v10
	v_mov_b32_e32 v153, v10
	v_mov_b32_e32 v162, v10
	v_mov_b32_e32 v163, v10
	v_mov_b32_e32 v164, v10
	v_mov_b32_e32 v165, v10
	v_mov_b32_e32 v166, v10
	v_mov_b32_e32 v167, v10
	v_mov_b32_e32 v168, v10
	v_mov_b32_e32 v169, v10
	s_add_i32 s74, s6, 2
	s_add_u32 s75, s0, 0x80
	s_addc_u32 s7, s1, 0
	s_cmp_eq_u32 s72, s6
	s_cselect_b32 s7, s89, s7
	s_cselect_b32 s6, s88, s75
	s_cselect_b32 s81, s23, s9
	s_cselect_b32 s80, s22, s8
	s_add_i32 s75, 0, 0x14000
	v_add_u32_e32 v74, s91, v221
	v_add_u32_e32 v102, s75, v221
.LBB0_259:
	ds_read_b128 v[58:61], v74
	ds_read_b128 v[66:69], v74 offset:1024
	ds_read_b128 v[70:73], v74 offset:2048
	ds_read_b128 v[74:77], v74 offset:3072
	ds_read_b128 v[90:93], v102
	ds_read_b128 v[94:97], v102 offset:1024
	ds_read_b128 v[98:101], v102 offset:2048
	ds_read_b128 v[102:105], v102 offset:3072
	v_lshl_add_u64 v[172:173], s[0:1], 0, v[180:181]
	s_add_i32 m0, s24, 0xc000
	ds_read_b128 v[184:187], v222
	ds_read_b128 v[188:191], v222 offset:1024
	ds_read_b128 v[192:195], v222 offset:2048
	ds_read_b128 v[196:199], v222 offset:3072
	ds_read_b128 v[200:203], v222 offset:4096
	ds_read_b128 v[224:227], v222 offset:5120
	ds_read_b128 v[228:231], v222 offset:6144
	ds_read_b128 v[232:235], v222 offset:7168
	global_load_lds_dwordx4 v[172:173], off
	v_lshl_add_u64 v[172:173], s[0:1], 0, v[182:183]
	s_add_i32 m0, s24, 0xe000
	s_nop 0
	global_load_lds_dwordx4 v[172:173], off
	s_waitcnt vmcnt(8)
	s_waitcnt lgkmcnt(0)
	s_barrier
; #define PG8_STAGE(bufoff, gbase, voff) do { _Pragma("unroll") for (int _i = 0; _i < 2; ++_i) \
;         __builtin_amdgcn_global_load_lds((const unsigned*)((const char*)(gbase) + (voff)[_i]), (LAS unsigned*)(lds + (bufoff) + ldsw + _i * 8192), 16, 0, 0); } while (0)
; #define PG8_LDA(dst, b, h) do { _Pragma("unroll") for (int m = 0; m < 4; ++m) _Pragma("unroll") for (int k = 0; k < 2; ++k) dst[m][k] = *(const LAS bf16x8*)(lds + PG8_SA(b, h) + aoff + m * 2048 + k * 1024); } while (0)
; #define PG8_LDB(dst, b, h) do { _Pragma("unroll") for (int n = 0; n < 2; ++n) _Pragma("unroll") for (int k = 0; k < 2; ++k) dst[n][k] = *(const LAS bf16x8*)(lds + PG8_SB(b, h) + boff + n * 2048 + k * 1024); } while (0)
; #define PG8_MMA(ai, bj, At, Bt) do { __builtin_amdgcn_s_setprio(1); _Pragma("unroll") for (int m = 0; m < 4; ++m) _Pragma("unroll") for (int n = 0; n < 2; ++n) _Pragma("unroll") for (int k = 0; k < 2; ++k) \
;         acc[ai][bj][m][n] = __builtin_amdgcn_mfma_f32_16x16x32_bf16(Bt[n][k], At[m][k], acc[ai][bj][m][n], 0, 0, 0); __builtin_amdgcn_s_setprio(0); } while (0)
; #define PG8_WAIT_V(n) asm volatile("s_waitcnt vmcnt(" #n ")" ::: "memory")
; #define PG8_WAIT_L(n) asm volatile("s_waitcnt lgkmcnt(" #n ")" ::: "memory")
; #define PG8_BAR __builtin_amdgcn_s_barrier()
; #define PG8_SCHED __builtin_amdgcn_sched_barrier(0)
; template <class Epi, bool ALIGN_EPI = true>
; __device__ __forceinline__ void gemm_phase(LAS unsigned char* lds, const Gemm g, const StaticOrder& S, const Epi& E) {
;     ...
;             PG8_WAIT_V(8); PG8_WAIT_L(0); PG8_BAR; PG8_MMA(0, 0, At, B0); PG8_MMA(0, 1, At, B1); PG8_BAR; PG8_SCHED;
;             PG8_LDA(At, 0, 1); PG8_STAGE(PG8_SB(0, 0), b2, voffB); PG8_STAGE(PG8_SB(0, 1), b2 + hsB, voffB); PG8_STAGE(PG8_SA(0, 0), a2, voffA);
;             PG8_WAIT_V(8); PG8_WAIT_L(0); PG8_BAR; PG8_MMA(1, 0, At, B0); PG8_MMA(1, 1, At, B1); PG8_BAR; PG8_SCHED;
;             PG8_LDB(B0, 1, 0); PG8_LDB(B1, 1, 1); PG8_SCHED; PG8_LDA(At, 1, 0); PG8_STAGE(PG8_SA(0, 1), a2 + hsA, voffA);
;             PG8_WAIT_V(8); PG8_WAIT_L(0); PG8_BAR; PG8_MMA(0, 0, At, B0); PG8_MMA(0, 1, At, B1); PG8_BAR; PG8_SCHED;
	s_setprio 1
	s_waitcnt lgkmcnt(0)
	v_mfma_f32_16x16x32_bf16 v[166:169], v[58:61], v[184:187], v[166:169]
	v_mfma_f32_16x16x32_bf16 v[162:165], v[70:73], v[184:187], v[162:165]
	v_mfma_f32_16x16x32_bf16 v[150:153], v[58:61], v[192:195], v[150:153]
	v_mfma_f32_16x16x32_bf16 v[146:149], v[70:73], v[192:195], v[146:149]
	v_mfma_f32_16x16x32_bf16 v[134:137], v[58:61], v[200:203], v[134:137]
	v_mfma_f32_16x16x32_bf16 v[130:133], v[70:73], v[200:203], v[130:133]
	v_mfma_f32_16x16x32_bf16 v[118:121], v[58:61], v[228:231], v[118:121]
	v_mfma_f32_16x16x32_bf16 v[114:117], v[70:73], v[228:231], v[114:117]
	v_mfma_f32_16x16x32_bf16 v[166:169], v[66:69], v[188:191], v[166:169]
	v_mfma_f32_16x16x32_bf16 v[162:165], v[74:77], v[188:191], v[162:165]
	v_mfma_f32_16x16x32_bf16 v[150:153], v[66:69], v[196:199], v[150:153]
	v_mfma_f32_16x16x32_bf16 v[146:149], v[74:77], v[196:199], v[146:149]
	v_mfma_f32_16x16x32_bf16 v[134:137], v[66:69], v[224:227], v[134:137]
	v_mfma_f32_16x16x32_bf16 v[130:133], v[74:77], v[224:227], v[130:133]
	v_mfma_f32_16x16x32_bf16 v[118:121], v[66:69], v[232:235], v[118:121]
	v_mfma_f32_16x16x32_bf16 v[114:117], v[74:77], v[232:235], v[114:117]
	s_setprio 0
	s_setprio 1
	v_mfma_f32_16x16x32_bf16 v[158:161], v[90:93], v[184:187], v[158:161]
	v_mfma_f32_16x16x32_bf16 v[154:157], v[98:101], v[184:187], v[154:157]
	v_mfma_f32_16x16x32_bf16 v[142:145], v[90:93], v[192:195], v[142:145]
	v_mfma_f32_16x16x32_bf16 v[138:141], v[98:101], v[192:195], v[138:141]
	v_mfma_f32_16x16x32_bf16 v[126:129], v[90:93], v[200:203], v[126:129]
	v_mfma_f32_16x16x32_bf16 v[122:125], v[98:101], v[200:203], v[122:125]
	v_mfma_f32_16x16x32_bf16 v[110:113], v[90:93], v[228:231], v[110:113]
	v_mfma_f32_16x16x32_bf16 v[106:109], v[98:101], v[228:231], v[106:109]
	v_mfma_f32_16x16x32_bf16 v[158:161], v[94:97], v[188:191], v[158:161]
	v_mfma_f32_16x16x32_bf16 v[154:157], v[102:105], v[188:191], v[154:157]
	v_mfma_f32_16x16x32_bf16 v[142:145], v[94:97], v[196:199], v[142:145]
	v_mfma_f32_16x16x32_bf16 v[138:141], v[102:105], v[196:199], v[138:141]
	v_mfma_f32_16x16x32_bf16 v[126:129], v[94:97], v[224:227], v[126:129]
	v_mfma_f32_16x16x32_bf16 v[122:125], v[102:105], v[224:227], v[122:125]
	v_mfma_f32_16x16x32_bf16 v[110:113], v[94:97], v[232:235], v[110:113]
	v_mfma_f32_16x16x32_bf16 v[106:109], v[102:105], v[232:235], v[106:109]
	s_setprio 0
	s_barrier
	s_add_i32 s78, s91, s11
	v_lshl_add_u64 v[172:173], s[80:81], 0, v[2:3]
	s_mov_b32 m0, s78
	ds_read_b128 v[184:187], v222 offset:16384
	ds_read_b128 v[188:191], v222 offset:17408
	ds_read_b128 v[192:195], v222 offset:18432
	ds_read_b128 v[196:199], v222 offset:19456
	ds_read_b128 v[200:203], v222 offset:20480
	ds_read_b128 v[224:227], v222 offset:21504
	ds_read_b128 v[228:231], v222 offset:22528
	ds_read_b128 v[232:235], v222 offset:23552
	global_load_lds_dwordx4 v[172:173], off
	s_add_i32 m0, s78, 0x2000
	v_lshl_add_u64 v[236:237], s[80:81], 0, v[178:179]
	s_add_u32 s80, s80, s96
	s_addc_u32 s81, s81, 0
	s_add_i32 s75, s75, s11
	global_load_lds_dwordx4 v[236:237], off
	v_lshl_add_u64 v[238:239], s[80:81], 0, v[2:3]
	s_mov_b32 m0, s75
	v_lshl_add_u64 v[240:241], s[80:81], 0, v[178:179]
	global_load_lds_dwordx4 v[238:239], off
	s_add_i32 m0, s75, 0x2000
	v_lshl_add_u64 v[244:245], s[6:7], 0, v[4:5]
	global_load_lds_dwordx4 v[240:241], off
	s_mov_b32 m0, s24
	v_lshl_add_u64 v[246:247], s[6:7], 0, v[176:177]
	global_load_lds_dwordx4 v[244:245], off
	s_mov_b32 m0, s25
	s_nop 0
	global_load_lds_dwordx4 v[246:247], off
	s_waitcnt vmcnt(8)
	s_waitcnt lgkmcnt(0)
	s_barrier
	s_setprio 1
	s_waitcnt lgkmcnt(0)
	v_mfma_f32_16x16x32_bf16 v[86:89], v[58:61], v[184:187], v[86:89]
	v_mfma_f32_16x16x32_bf16 v[82:85], v[70:73], v[184:187], v[82:85]
	v_mfma_f32_16x16x32_bf16 v[54:57], v[58:61], v[192:195], v[54:57]
	v_mfma_f32_16x16x32_bf16 v[50:53], v[70:73], v[192:195], v[50:53]
	v_mfma_f32_16x16x32_bf16 v[38:41], v[58:61], v[200:203], v[38:41]
	v_mfma_f32_16x16x32_bf16 v[34:37], v[70:73], v[200:203], v[34:37]
	v_mfma_f32_16x16x32_bf16 v[22:25], v[58:61], v[228:231], v[22:25]
	v_mfma_f32_16x16x32_bf16 v[18:21], v[70:73], v[228:231], v[18:21]
	v_mfma_f32_16x16x32_bf16 v[86:89], v[66:69], v[188:191], v[86:89]
	v_mfma_f32_16x16x32_bf16 v[82:85], v[74:77], v[188:191], v[82:85]
	v_mfma_f32_16x16x32_bf16 v[54:57], v[66:69], v[196:199], v[54:57]
	v_mfma_f32_16x16x32_bf16 v[50:53], v[74:77], v[196:199], v[50:53]
	v_mfma_f32_16x16x32_bf16 v[38:41], v[66:69], v[224:227], v[38:41]
	v_mfma_f32_16x16x32_bf16 v[34:37], v[74:77], v[224:227], v[34:37]
	v_mfma_f32_16x16x32_bf16 v[22:25], v[66:69], v[232:235], v[22:25]
	v_mfma_f32_16x16x32_bf16 v[18:21], v[74:77], v[232:235], v[18:21]
	s_setprio 0
	s_setprio 1
	v_mfma_f32_16x16x32_bf16 v[62:65], v[98:101], v[184:187], v[62:65]
	v_mfma_f32_16x16x32_bf16 v[46:49], v[90:93], v[192:195], v[46:49]
	v_mfma_f32_16x16x32_bf16 v[42:45], v[98:101], v[192:195], v[42:45]
	v_mfma_f32_16x16x32_bf16 v[30:33], v[90:93], v[200:203], v[30:33]
	v_mfma_f32_16x16x32_bf16 v[26:29], v[98:101], v[200:203], v[26:29]
	v_mfma_f32_16x16x32_bf16 v[14:17], v[90:93], v[228:231], v[14:17]
	v_mfma_f32_16x16x32_bf16 v[10:13], v[98:101], v[228:231], v[10:13]
	v_mfma_f32_16x16x32_bf16 v[58:61], v[90:93], v[184:187], v[78:81]
	v_mfma_f32_16x16x32_bf16 v[62:65], v[102:105], v[188:191], v[62:65]
	v_mfma_f32_16x16x32_bf16 v[46:49], v[94:97], v[196:199], v[46:49]
	v_mfma_f32_16x16x32_bf16 v[42:45], v[102:105], v[196:199], v[42:45]
	v_mfma_f32_16x16x32_bf16 v[30:33], v[94:97], v[224:227], v[30:33]
	v_mfma_f32_16x16x32_bf16 v[26:29], v[102:105], v[224:227], v[26:29]
	v_mfma_f32_16x16x32_bf16 v[14:17], v[94:97], v[232:235], v[14:17]
	v_mfma_f32_16x16x32_bf16 v[10:13], v[102:105], v[232:235], v[10:13]
	v_mfma_f32_16x16x32_bf16 v[58:61], v[94:97], v[188:191], v[58:61]
	s_setprio 0
	s_barrier
; #define PG8_STAGE(bufoff, gbase, voff) do { _Pragma("unroll") for (int _i = 0; _i < 2; ++_i) \
;         __builtin_amdgcn_global_load_lds((const unsigned*)((const char*)(gbase) + (voff)[_i]), (LAS unsigned*)(lds + (bufoff) + ldsw + _i * 8192), 16, 0, 0); } while (0)
; #define PG8_LDA(dst, b, h) do { _Pragma("unroll") for (int m = 0; m < 4; ++m) _Pragma("unroll") for (int k = 0; k < 2; ++k) dst[m][k] = *(const LAS bf16x8*)(lds + PG8_SA(b, h) + aoff + m * 2048 + k * 1024); } while (0)
; #define PG8_LDB(dst, b, h) do { _Pragma("unroll") for (int n = 0; n < 2; ++n) _Pragma("unroll") for (int k = 0; k < 2; ++k) dst[n][k] = *(const LAS bf16x8*)(lds + PG8_SB(b, h) + boff + n * 2048 + k * 1024); } while (0)
; #define PG8_MMA(ai, bj, At, Bt) do { __builtin_amdgcn_s_setprio(1); _Pragma("unroll") for (int m = 0; m < 4; ++m) _Pragma("unroll") for (int n = 0; n < 2; ++n) _Pragma("unroll") for (int k = 0; k < 2; ++k) \
;         acc[ai][bj][m][n] = __builtin_amdgcn_mfma_f32_16x16x32_bf16(Bt[n][k], At[m][k], acc[ai][bj][m][n], 0, 0, 0); __builtin_amdgcn_s_setprio(0); } while (0)
; #define PG8_WAIT_V(n) asm volatile("s_waitcnt vmcnt(" #n ")" ::: "memory")
; #define PG8_WAIT_L(n) asm volatile("s_waitcnt lgkmcnt(" #n ")" ::: "memory")
; #define PG8_BAR __builtin_amdgcn_s_barrier()
; #define PG8_SCHED __builtin_amdgcn_sched_barrier(0)
; template <class Epi, bool ALIGN_EPI = true>
; __device__ __forceinline__ void gemm_phase(LAS unsigned char* lds, const Gemm g, const StaticOrder& S, const Epi& E) {
;     ...
;             PG8_LDB(B0, 1, 0); PG8_LDB(B1, 1, 1); PG8_SCHED; PG8_LDA(At, 1, 0); PG8_STAGE(PG8_SA(0, 1), a2 + hsA, voffA);
;             PG8_WAIT_V(8); PG8_WAIT_L(0); PG8_BAR; PG8_MMA(0, 0, At, B0); PG8_MMA(0, 1, At, B1); PG8_BAR; PG8_SCHED;
	s_add_i32 s75, 0, 0x18000
	s_add_i32 s78, 0, 0x1c000
	v_add_u32_e32 v78, s75, v221
	v_add_u32_e32 v102, s78, v221
	ds_read_b128 v[66:69], v78
	ds_read_b128 v[70:73], v78 offset:1024
	ds_read_b128 v[74:77], v78 offset:2048
	ds_read_b128 v[78:81], v78 offset:3072
	ds_read_b128 v[90:93], v102
	ds_read_b128 v[94:97], v102 offset:1024
	ds_read_b128 v[98:101], v102 offset:2048
	ds_read_b128 v[102:105], v102 offset:3072
	s_add_u32 s6, s6, s14
	s_addc_u32 s7, s7, 0
	s_mov_b32 m0, s26
	v_lshl_add_u64 v[248:249], s[6:7], 0, v[4:5]
	ds_read_b128 v[184:187], v222 offset:32768
	ds_read_b128 v[188:191], v222 offset:33792
	ds_read_b128 v[192:195], v222 offset:34816
	ds_read_b128 v[196:199], v222 offset:35840
	ds_read_b128 v[200:203], v222 offset:36864
	ds_read_b128 v[224:227], v222 offset:37888
	ds_read_b128 v[228:231], v222 offset:38912
	ds_read_b128 v[232:235], v222 offset:39936
	global_load_lds_dwordx4 v[248:249], off
	v_lshl_add_u64 v[248:249], s[6:7], 0, v[176:177]
	s_mov_b32 m0, s36
	s_nop 0
	global_load_lds_dwordx4 v[248:249], off
	s_waitcnt vmcnt(8)
	s_waitcnt lgkmcnt(0)
	s_barrier
	s_setprio 1
	s_waitcnt lgkmcnt(0)
	v_mfma_f32_16x16x32_bf16 v[166:169], v[66:69], v[184:187], v[166:169]
	v_mfma_f32_16x16x32_bf16 v[162:165], v[74:77], v[184:187], v[162:165]
	v_mfma_f32_16x16x32_bf16 v[150:153], v[66:69], v[192:195], v[150:153]
	v_mfma_f32_16x16x32_bf16 v[146:149], v[74:77], v[192:195], v[146:149]
	v_mfma_f32_16x16x32_bf16 v[134:137], v[66:69], v[200:203], v[134:137]
	v_mfma_f32_16x16x32_bf16 v[130:133], v[74:77], v[200:203], v[130:133]
	v_mfma_f32_16x16x32_bf16 v[118:121], v[66:69], v[228:231], v[118:121]
	v_mfma_f32_16x16x32_bf16 v[114:117], v[74:77], v[228:231], v[114:117]
	v_mfma_f32_16x16x32_bf16 v[166:169], v[70:73], v[188:191], v[166:169]
	v_mfma_f32_16x16x32_bf16 v[162:165], v[78:81], v[188:191], v[162:165]
	v_mfma_f32_16x16x32_bf16 v[150:153], v[70:73], v[196:199], v[150:153]
	v_mfma_f32_16x16x32_bf16 v[146:149], v[78:81], v[196:199], v[146:149]
	v_mfma_f32_16x16x32_bf16 v[134:137], v[70:73], v[224:227], v[134:137]
	v_mfma_f32_16x16x32_bf16 v[130:133], v[78:81], v[224:227], v[130:133]
	v_mfma_f32_16x16x32_bf16 v[118:121], v[70:73], v[232:235], v[118:121]
	v_mfma_f32_16x16x32_bf16 v[114:117], v[78:81], v[232:235], v[114:117]
	s_setprio 0
	s_setprio 1
	v_mfma_f32_16x16x32_bf16 v[158:161], v[90:93], v[184:187], v[158:161]
	v_mfma_f32_16x16x32_bf16 v[154:157], v[98:101], v[184:187], v[154:157]
	v_mfma_f32_16x16x32_bf16 v[142:145], v[90:93], v[192:195], v[142:145]
	v_mfma_f32_16x16x32_bf16 v[138:141], v[98:101], v[192:195], v[138:141]
	v_mfma_f32_16x16x32_bf16 v[126:129], v[90:93], v[200:203], v[126:129]
	v_mfma_f32_16x16x32_bf16 v[122:125], v[98:101], v[200:203], v[122:125]
	v_mfma_f32_16x16x32_bf16 v[110:113], v[90:93], v[228:231], v[110:113]
	v_mfma_f32_16x16x32_bf16 v[106:109], v[98:101], v[228:231], v[106:109]
	v_mfma_f32_16x16x32_bf16 v[158:161], v[94:97], v[188:191], v[158:161]
	v_mfma_f32_16x16x32_bf16 v[154:157], v[102:105], v[188:191], v[154:157]
	v_mfma_f32_16x16x32_bf16 v[142:145], v[94:97], v[196:199], v[142:145]
	v_mfma_f32_16x16x32_bf16 v[138:141], v[102:105], v[196:199], v[138:141]
	v_mfma_f32_16x16x32_bf16 v[126:129], v[94:97], v[224:227], v[126:129]
	v_mfma_f32_16x16x32_bf16 v[122:125], v[102:105], v[224:227], v[122:125]
	v_mfma_f32_16x16x32_bf16 v[110:113], v[94:97], v[232:235], v[110:113]
	v_mfma_f32_16x16x32_bf16 v[106:109], v[102:105], v[232:235], v[106:109]
	s_setprio 0
	s_barrier
; #define PG8_STAGE(bufoff, gbase, voff) do { _Pragma("unroll") for (int _i = 0; _i < 2; ++_i) \
;         __builtin_amdgcn_global_load_lds((const unsigned*)((const char*)(gbase) + (voff)[_i]), (LAS unsigned*)(lds + (bufoff) + ldsw + _i * 8192), 16, 0, 0); } while (0)
; #define PG8_LDA(dst, b, h) do { _Pragma("unroll") for (int m = 0; m < 4; ++m) _Pragma("unroll") for (int k = 0; k < 2; ++k) dst[m][k] = *(const LAS bf16x8*)(lds + PG8_SA(b, h) + aoff + m * 2048 + k * 1024); } while (0)
; #define PG8_MMA(ai, bj, At, Bt) do { __builtin_amdgcn_s_setprio(1); _Pragma("unroll") for (int m = 0; m < 4; ++m) _Pragma("unroll") for (int n = 0; n < 2; ++n) _Pragma("unroll") for (int k = 0; k < 2; ++k) \
;         acc[ai][bj][m][n] = __builtin_amdgcn_mfma_f32_16x16x32_bf16(Bt[n][k], At[m][k], acc[ai][bj][m][n], 0, 0, 0); __builtin_amdgcn_s_setprio(0); } while (0)
; #define PG8_WAIT_V(n) asm volatile("s_waitcnt vmcnt(" #n ")" ::: "memory")
; #define PG8_WAIT_L(n) asm volatile("s_waitcnt lgkmcnt(" #n ")" ::: "memory")
; #define PG8_BAR __builtin_amdgcn_s_barrier()
; #define PG8_SCHED __builtin_amdgcn_sched_barrier(0)
; template <class Epi, bool ALIGN_EPI = true>
; __device__ __forceinline__ void gemm_phase(LAS unsigned char* lds, const Gemm g, const StaticOrder& S, const Epi& E) {
;     ...
;         for (int t = 0; t < nt; t += 2) {
;             const bool last = (t == nt - 2);
;             const char* a1 = cA + (size_t)(t + 1) * kstep;
;             const char* a2 = last ? nA : cA + (size_t)(t + 2) * kstep; const char* b2 = last ? nB : cB + (size_t)(t + 2) * kstep;
;             const char* a3 = a2 + kstep; const char* b3 = b2 + kstep;
;     ...
;             PG8_WAIT_V(8); PG8_WAIT_L(0); PG8_BAR; PG8_MMA(0, 0, At, B0); PG8_MMA(0, 1, At, B1); PG8_BAR; PG8_SCHED;
;             PG8_LDA(At, 1, 1); PG8_STAGE(PG8_SB(1, 0), b3, voffB); PG8_STAGE(PG8_SB(1, 1), b3 + hsB, voffB); PG8_STAGE(PG8_SA(1, 0), a3, voffA);
;             PG8_WAIT_V(8); PG8_WAIT_L(0); PG8_BAR; PG8_MMA(1, 0, At, B0); PG8_MMA(1, 1, At, B1); PG8_BAR; PG8_SCHED;
;         }
	s_add_i32 s6, s75, s11
	v_lshl_add_u64 v[172:173], v[172:173], 0, s[70:71]
	s_mov_b32 m0, s6
	ds_read_b128 v[184:187], v222 offset:49152
	ds_read_b128 v[188:191], v222 offset:50176
	ds_read_b128 v[192:195], v222 offset:51200
	ds_read_b128 v[196:199], v222 offset:52224
	ds_read_b128 v[200:203], v222 offset:53248
	ds_read_b128 v[224:227], v222 offset:54272
	ds_read_b128 v[228:231], v222 offset:55296
	ds_read_b128 v[232:235], v222 offset:56320
	global_load_lds_dwordx4 v[172:173], off
	v_lshl_add_u64 v[172:173], v[236:237], 0, s[70:71]
	s_add_i32 m0, s6, 0x2000
	s_add_i32 s6, s78, s11
	global_load_lds_dwordx4 v[172:173], off
	v_lshl_add_u64 v[172:173], v[238:239], 0, s[70:71]
	s_mov_b32 m0, s6
	s_nop 0
	global_load_lds_dwordx4 v[172:173], off
	v_lshl_add_u64 v[172:173], v[240:241], 0, s[70:71]
	s_add_i32 m0, s6, 0x2000
	s_nop 0
	global_load_lds_dwordx4 v[172:173], off
	v_lshl_add_u64 v[172:173], v[244:245], 0, s[70:71]
	s_mov_b32 m0, s69
	s_nop 0
	global_load_lds_dwordx4 v[172:173], off
	v_lshl_add_u64 v[172:173], v[246:247], 0, s[70:71]
	s_mov_b32 m0, s73
	s_nop 0
	global_load_lds_dwordx4 v[172:173], off
	s_waitcnt vmcnt(8)
	s_waitcnt lgkmcnt(0)
	s_barrier
	s_setprio 1
	s_waitcnt lgkmcnt(0)
	v_mfma_f32_16x16x32_bf16 v[86:89], v[66:69], v[184:187], v[86:89]
	v_mfma_f32_16x16x32_bf16 v[82:85], v[74:77], v[184:187], v[82:85]
	v_mfma_f32_16x16x32_bf16 v[54:57], v[66:69], v[192:195], v[54:57]
	v_mfma_f32_16x16x32_bf16 v[50:53], v[74:77], v[192:195], v[50:53]
	v_mfma_f32_16x16x32_bf16 v[38:41], v[66:69], v[200:203], v[38:41]
	v_mfma_f32_16x16x32_bf16 v[34:37], v[74:77], v[200:203], v[34:37]
	v_mfma_f32_16x16x32_bf16 v[22:25], v[66:69], v[228:231], v[22:25]
	v_mfma_f32_16x16x32_bf16 v[18:21], v[74:77], v[228:231], v[18:21]
	v_mfma_f32_16x16x32_bf16 v[86:89], v[70:73], v[188:191], v[86:89]
	v_mfma_f32_16x16x32_bf16 v[82:85], v[78:81], v[188:191], v[82:85]
	v_mfma_f32_16x16x32_bf16 v[54:57], v[70:73], v[196:199], v[54:57]
	v_mfma_f32_16x16x32_bf16 v[50:53], v[78:81], v[196:199], v[50:53]
	v_mfma_f32_16x16x32_bf16 v[38:41], v[70:73], v[224:227], v[38:41]
	v_mfma_f32_16x16x32_bf16 v[34:37], v[78:81], v[224:227], v[34:37]
	v_mfma_f32_16x16x32_bf16 v[22:25], v[70:73], v[232:235], v[22:25]
	v_mfma_f32_16x16x32_bf16 v[18:21], v[78:81], v[232:235], v[18:21]
	s_setprio 0
	s_setprio 1
	v_mfma_f32_16x16x32_bf16 v[58:61], v[90:93], v[184:187], v[58:61]
	v_mfma_f32_16x16x32_bf16 v[78:81], v[94:97], v[188:191], v[58:61]
	v_mfma_f32_16x16x32_bf16 v[58:61], v[98:101], v[184:187], v[62:65]
	v_mfma_f32_16x16x32_bf16 v[46:49], v[90:93], v[192:195], v[46:49]
	v_mfma_f32_16x16x32_bf16 v[42:45], v[98:101], v[192:195], v[42:45]
	v_mfma_f32_16x16x32_bf16 v[30:33], v[90:93], v[200:203], v[30:33]
	v_mfma_f32_16x16x32_bf16 v[26:29], v[98:101], v[200:203], v[26:29]
	v_mfma_f32_16x16x32_bf16 v[14:17], v[90:93], v[228:231], v[14:17]
	v_mfma_f32_16x16x32_bf16 v[10:13], v[98:101], v[228:231], v[10:13]
	v_mfma_f32_16x16x32_bf16 v[62:65], v[102:105], v[188:191], v[58:61]
	v_mfma_f32_16x16x32_bf16 v[46:49], v[94:97], v[196:199], v[46:49]
	v_mfma_f32_16x16x32_bf16 v[42:45], v[102:105], v[196:199], v[42:45]
	v_mfma_f32_16x16x32_bf16 v[30:33], v[94:97], v[224:227], v[30:33]
	v_mfma_f32_16x16x32_bf16 v[26:29], v[102:105], v[224:227], v[26:29]
	v_mfma_f32_16x16x32_bf16 v[14:17], v[94:97], v[232:235], v[14:17]
	v_mfma_f32_16x16x32_bf16 v[10:13], v[102:105], v[232:235], v[10:13]
	s_setprio 0
	s_add_u32 s0, s0, 0x100
	s_addc_u32 s1, s1, 0
	s_add_u32 s8, s8, 0x100
	s_addc_u32 s9, s9, 0
	s_cmp_ge_u32 s74, s95
	s_mov_b32 s6, s74
	s_cbranch_scc1 .Lrot_exit_259
	s_add_i32 s74, s6, 2
	s_add_u32 s75, s0, 0x80
	s_addc_u32 s7, s1, 0
	s_cmp_eq_u32 s72, s6
	s_cselect_b32 s7, s89, s7
	s_cselect_b32 s6, s88, s75
	s_cselect_b32 s81, s23, s9
	s_cselect_b32 s80, s22, s8
	s_add_i32 s75, 0, 0x14000
	v_add_u32_e32 v74, s91, v221
	v_add_u32_e32 v102, s75, v221
	s_barrier
	s_branch .LBB0_259
.Lrot_exit_259:
	s_barrier
	v_readlane_b32 s0, v255, 0
	v_readlane_b32 s1, v255, 1
	s_and_b64 vcc, exec, s[0:1]
	s_cbranch_vccz .LBB0_262
	s_barrier

; #define PG8_STAGE(bufoff, gbase, voff) do { _Pragma("unroll") for (int _i = 0; _i < 2; ++_i) \
;         __builtin_amdgcn_global_load_lds((const unsigned*)((const char*)(gbase) + (voff)[_i]), (LAS unsigned*)(lds + (bufoff) + ldsw + _i * 8192), 16, 0, 0); } while (0)
; #define PG8_LDA(dst, b, h) do { _Pragma("unroll") for (int m = 0; m < 4; ++m) _Pragma("unroll") for (int k = 0; k < 2; ++k) dst[m][k] = *(const LAS bf16x8*)(lds + PG8_SA(b, h) + aoff + m * 2048 + k * 1024); } while (0)
; #define PG8_LDB(dst, b, h) do { _Pragma("unroll") for (int n = 0; n < 2; ++n) _Pragma("unroll") for (int k = 0; k < 2; ++k) dst[n][k] = *(const LAS bf16x8*)(lds + PG8_SB(b, h) + boff + n * 2048 + k * 1024); } while (0)
; #define PG8_MMA(ai, bj, At, Bt) do { __builtin_amdgcn_s_setprio(1); _Pragma("unroll") for (int m = 0; m < 4; ++m) _Pragma("unroll") for (int n = 0; n < 2; ++n) _Pragma("unroll") for (int k = 0; k < 2; ++k) \
;         acc[ai][bj][m][n] = __builtin_amdgcn_mfma_f32_16x16x32_bf16(Bt[n][k], At[m][k], acc[ai][bj][m][n], 0, 0, 0); __builtin_amdgcn_s_setprio(0); } while (0)
; template <class Epi, bool ALIGN_EPI = true>
; __device__ __forceinline__ void gemm_phase(LAS unsigned char* lds, const Gemm g, const StaticOrder& S, const Epi& E) {
;     ...
;         const bool has_next = S.next(ui + 1, nxt);
;         const char* nA = has_next ? (const char*)g.A + (size_t)nxt.pm * tsA : cA; const char* nB = has_next ? (const char*)g.Bt + (size_t)nxt.pn * tsB : cB;
;         for (int t = 0; t < nt; t += 2) {
;             const bool last = (t == nt - 2);
;             const char* a1 = cA + (size_t)(t + 1) * kstep;
;             const char* a2 = last ? nA : cA + (size_t)(t + 2) * kstep; const char* b2 = last ? nB : cB + (size_t)(t + 2) * kstep;
;             const char* a3 = a2 + kstep; const char* b3 = b2 + kstep;
;             PG8_LDB(B0, 0, 0); PG8_LDB(B1, 0, 1); PG8_SCHED; PG8_LDA(At, 0, 0); PG8_STAGE(PG8_SA(1, 1), a1 + hsA, voffA);
;             PG8_WAIT_V(8); PG8_WAIT_L(0); PG8_BAR; PG8_MMA(0, 0, At, B0); PG8_MMA(0, 1, At, B1); PG8_BAR; PG8_SCHED;
;     ...
; #pragma unroll
;         for (int a = 0; a < 2; ++a)
; #pragma unroll
;             for (int b = 0; b < 2; ++b)
; #pragma unroll
;                 for (int m = 0; m < 4; ++m)
; #pragma unroll
;                     for (int n = 0; n < 2; ++n) acc[a][b][m][n] = (f32x4){0.f, 0.f, 0.f, 0.f};
;         cur = nxt; cA = nA; cB = nB; ++ui;
.LBB0_296:
	s_add_u32 s0, s86, 0x80
	s_addc_u32 s1, s87, 0
	s_add_u32 s86, s82, 0x100
	v_mov_b32_e32 v10, 0
	s_addc_u32 s87, s83, 0
	s_mov_b32 s82, 0
	v_mov_b32_e32 v11, v10
	v_mov_b32_e32 v12, v10
	v_mov_b32_e32 v13, v10
	v_mov_b32_e32 v14, v10
	v_mov_b32_e32 v15, v10
	v_mov_b32_e32 v16, v10
	v_mov_b32_e32 v17, v10
	v_mov_b32_e32 v26, v10
	v_mov_b32_e32 v27, v10
	v_mov_b32_e32 v28, v10
	v_mov_b32_e32 v29, v10
	v_mov_b32_e32 v30, v10
	v_mov_b32_e32 v31, v10
	v_mov_b32_e32 v32, v10
	v_mov_b32_e32 v33, v10
	v_mov_b32_e32 v42, v10
	v_mov_b32_e32 v43, v10
	v_mov_b32_e32 v44, v10
	v_mov_b32_e32 v45, v10
	v_mov_b32_e32 v46, v10
	v_mov_b32_e32 v47, v10
	v_mov_b32_e32 v48, v10
	v_mov_b32_e32 v49, v10
	v_mov_b32_e32 v58, v10
	v_mov_b32_e32 v59, v10
	v_mov_b32_e32 v60, v10
	v_mov_b32_e32 v61, v10
	v_mov_b32_e32 v62, v10
	v_mov_b32_e32 v63, v10
	v_mov_b32_e32 v64, v10
	v_mov_b32_e32 v65, v10
	v_mov_b32_e32 v18, v10
	v_mov_b32_e32 v19, v10
	v_mov_b32_e32 v20, v10
	v_mov_b32_e32 v21, v10
	v_mov_b32_e32 v22, v10
	v_mov_b32_e32 v23, v10
	v_mov_b32_e32 v24, v10
	v_mov_b32_e32 v25, v10
	v_mov_b32_e32 v34, v10
	v_mov_b32_e32 v35, v10
	v_mov_b32_e32 v36, v10
	v_mov_b32_e32 v37, v10
	v_mov_b32_e32 v38, v10
	v_mov_b32_e32 v39, v10
	v_mov_b32_e32 v40, v10
	v_mov_b32_e32 v41, v10
	v_mov_b32_e32 v50, v10
	v_mov_b32_e32 v51, v10
	v_mov_b32_e32 v52, v10
	v_mov_b32_e32 v53, v10
	v_mov_b32_e32 v54, v10
	v_mov_b32_e32 v55, v10
	v_mov_b32_e32 v56, v10
	v_mov_b32_e32 v57, v10
	v_mov_b32_e32 v66, v10
	v_mov_b32_e32 v67, v10
	v_mov_b32_e32 v68, v10
	v_mov_b32_e32 v69, v10
	v_mov_b32_e32 v70, v10
	v_mov_b32_e32 v71, v10
	v_mov_b32_e32 v72, v10
	v_mov_b32_e32 v73, v10
	v_mov_b32_e32 v74, v10
	v_mov_b32_e32 v75, v10
	v_mov_b32_e32 v76, v10
	v_mov_b32_e32 v77, v10
	v_mov_b32_e32 v78, v10
	v_mov_b32_e32 v79, v10
	v_mov_b32_e32 v80, v10
	v_mov_b32_e32 v81, v10
	v_mov_b32_e32 v90, v10
	v_mov_b32_e32 v91, v10
	v_mov_b32_e32 v92, v10
	v_mov_b32_e32 v93, v10
	v_mov_b32_e32 v94, v10
	v_mov_b32_e32 v95, v10
	v_mov_b32_e32 v96, v10
	v_mov_b32_e32 v97, v10
	v_mov_b32_e32 v106, v10
	v_mov_b32_e32 v107, v10
	v_mov_b32_e32 v108, v10
	v_mov_b32_e32 v109, v10
	v_mov_b32_e32 v110, v10
	v_mov_b32_e32 v111, v10
	v_mov_b32_e32 v112, v10
	v_mov_b32_e32 v113, v10
	v_mov_b32_e32 v122, v10
	v_mov_b32_e32 v123, v10
	v_mov_b32_e32 v124, v10
	v_mov_b32_e32 v125, v10
	v_mov_b32_e32 v126, v10
	v_mov_b32_e32 v127, v10
	v_mov_b32_e32 v128, v10
	v_mov_b32_e32 v129, v10
	v_mov_b32_e32 v82, v10
	v_mov_b32_e32 v83, v10
	v_mov_b32_e32 v84, v10
	v_mov_b32_e32 v85, v10
	v_mov_b32_e32 v86, v10
	v_mov_b32_e32 v87, v10
	v_mov_b32_e32 v88, v10
	v_mov_b32_e32 v89, v10
	v_mov_b32_e32 v98, v10
	v_mov_b32_e32 v99, v10
	v_mov_b32_e32 v100, v10
	v_mov_b32_e32 v101, v10
	v_mov_b32_e32 v102, v10
	v_mov_b32_e32 v103, v10
	v_mov_b32_e32 v104, v10
	v_mov_b32_e32 v105, v10
	v_mov_b32_e32 v114, v10
	v_mov_b32_e32 v115, v10
	v_mov_b32_e32 v116, v10
	v_mov_b32_e32 v117, v10
	v_mov_b32_e32 v118, v10
	v_mov_b32_e32 v119, v10
	v_mov_b32_e32 v120, v10
	v_mov_b32_e32 v121, v10
	v_mov_b32_e32 v130, v10
	v_mov_b32_e32 v131, v10
	v_mov_b32_e32 v132, v10
	v_mov_b32_e32 v133, v10
	v_mov_b32_e32 v134, v10
	v_mov_b32_e32 v135, v10
	v_mov_b32_e32 v136, v10
	v_mov_b32_e32 v137, v10
	s_add_i32 vcc_lo, s82, 2
	s_add_u32 s80, s0, 0x80
	s_addc_u32 s81, s1, 0
	s_cmp_eq_u32 s72, s82
	s_cselect_b32 s83, s25, s81
	s_cselect_b32 s82, s24, s80
	v_add_u32_e32 v146, s91, v153
	s_cselect_b32 s81, s85, s87
	s_cselect_b32 s80, s84, s86
	s_add_i32 vcc_hi, 0, 0x14000
.LBB0_297:
	ds_read_b128 v[156:159], v146
	ds_read_b128 v[160:163], v146 offset:1024
	ds_read_b128 v[164:167], v146 offset:2048
	ds_read_b128 v[176:179], v146 offset:3072
	v_add_u32_e32 v146, vcc_hi, v153
	ds_read_b128 v[180:183], v146
	ds_read_b128 v[184:187], v146 offset:1024
	ds_read_b128 v[188:191], v146 offset:2048
	ds_read_b128 v[192:195], v146 offset:3072
	v_lshl_add_u64 v[146:147], s[0:1], 0, v[142:143]
	s_add_i32 m0, s26, 0xc000
	ds_read_b128 v[196:199], v154
	ds_read_b128 v[200:203], v154 offset:1024
	ds_read_b128 v[220:223], v154 offset:2048
	ds_read_b128 v[224:227], v154 offset:3072
	ds_read_b128 v[228:231], v154 offset:4096
	ds_read_b128 v[232:235], v154 offset:5120
	ds_read_b128 v[236:239], v154 offset:6144
	ds_read_b128 v[244:247], v154 offset:7168
	global_load_lds_dwordx4 v[146:147], off
	v_lshl_add_u64 v[146:147], s[0:1], 0, v[144:145]
	s_add_i32 m0, s26, 0xe000
	s_nop 0
	global_load_lds_dwordx4 v[146:147], off
	s_waitcnt vmcnt(8)
	s_waitcnt lgkmcnt(0)
	s_barrier
; #define PG8_STAGE(bufoff, gbase, voff) do { _Pragma("unroll") for (int _i = 0; _i < 2; ++_i) \
;         __builtin_amdgcn_global_load_lds((const unsigned*)((const char*)(gbase) + (voff)[_i]), (LAS unsigned*)(lds + (bufoff) + ldsw + _i * 8192), 16, 0, 0); } while (0)
; #define PG8_LDA(dst, b, h) do { _Pragma("unroll") for (int m = 0; m < 4; ++m) _Pragma("unroll") for (int k = 0; k < 2; ++k) dst[m][k] = *(const LAS bf16x8*)(lds + PG8_SA(b, h) + aoff + m * 2048 + k * 1024); } while (0)
; #define PG8_MMA(ai, bj, At, Bt) do { __builtin_amdgcn_s_setprio(1); _Pragma("unroll") for (int m = 0; m < 4; ++m) _Pragma("unroll") for (int n = 0; n < 2; ++n) _Pragma("unroll") for (int k = 0; k < 2; ++k) \
;         acc[ai][bj][m][n] = __builtin_amdgcn_mfma_f32_16x16x32_bf16(Bt[n][k], At[m][k], acc[ai][bj][m][n], 0, 0, 0); __builtin_amdgcn_s_setprio(0); } while (0)
; #define PG8_WAIT_V(n) asm volatile("s_waitcnt vmcnt(" #n ")" ::: "memory")
; #define PG8_WAIT_L(n) asm volatile("s_waitcnt lgkmcnt(" #n ")" ::: "memory")
; #define PG8_BAR __builtin_amdgcn_s_barrier()
; #define PG8_SCHED __builtin_amdgcn_sched_barrier(0)
; template <class Epi, bool ALIGN_EPI = true>
; __device__ __forceinline__ void gemm_phase(LAS unsigned char* lds, const Gemm g, const StaticOrder& S, const Epi& E) {
;     ...
;             PG8_WAIT_V(8); PG8_WAIT_L(0); PG8_BAR; PG8_MMA(0, 0, At, B0); PG8_MMA(0, 1, At, B1); PG8_BAR; PG8_SCHED;
;             PG8_LDA(At, 0, 1); PG8_STAGE(PG8_SB(0, 0), b2, voffB); PG8_STAGE(PG8_SB(0, 1), b2 + hsB, voffB); PG8_STAGE(PG8_SA(0, 0), a2, voffA);
;             PG8_WAIT_V(8); PG8_WAIT_L(0); PG8_BAR; PG8_MMA(1, 0, At, B0); PG8_MMA(1, 1, At, B1); PG8_BAR; PG8_SCHED;
	s_setprio 1
	s_waitcnt lgkmcnt(0)
	v_mfma_f32_16x16x32_bf16 v[134:137], v[156:159], v[196:199], v[134:137]
	v_mfma_f32_16x16x32_bf16 v[130:133], v[164:167], v[196:199], v[130:133]
	v_mfma_f32_16x16x32_bf16 v[118:121], v[156:159], v[220:223], v[118:121]
	v_mfma_f32_16x16x32_bf16 v[114:117], v[164:167], v[220:223], v[114:117]
	v_mfma_f32_16x16x32_bf16 v[102:105], v[156:159], v[228:231], v[102:105]
	v_mfma_f32_16x16x32_bf16 v[98:101], v[164:167], v[228:231], v[98:101]
	v_mfma_f32_16x16x32_bf16 v[86:89], v[156:159], v[236:239], v[86:89]
	v_mfma_f32_16x16x32_bf16 v[82:85], v[164:167], v[236:239], v[82:85]
	v_mfma_f32_16x16x32_bf16 v[134:137], v[160:163], v[200:203], v[134:137]
	v_mfma_f32_16x16x32_bf16 v[130:133], v[176:179], v[200:203], v[130:133]
	v_mfma_f32_16x16x32_bf16 v[118:121], v[160:163], v[224:227], v[118:121]
	v_mfma_f32_16x16x32_bf16 v[114:117], v[176:179], v[224:227], v[114:117]
	v_mfma_f32_16x16x32_bf16 v[102:105], v[160:163], v[232:235], v[102:105]
	v_mfma_f32_16x16x32_bf16 v[98:101], v[176:179], v[232:235], v[98:101]
	v_mfma_f32_16x16x32_bf16 v[86:89], v[160:163], v[244:247], v[86:89]
	v_mfma_f32_16x16x32_bf16 v[82:85], v[176:179], v[244:247], v[82:85]
	s_setprio 0
	s_setprio 1
	v_mfma_f32_16x16x32_bf16 v[126:129], v[180:183], v[196:199], v[126:129]
	v_mfma_f32_16x16x32_bf16 v[122:125], v[188:191], v[196:199], v[122:125]
	v_mfma_f32_16x16x32_bf16 v[110:113], v[180:183], v[220:223], v[110:113]
	v_mfma_f32_16x16x32_bf16 v[106:109], v[188:191], v[220:223], v[106:109]
	v_mfma_f32_16x16x32_bf16 v[94:97], v[180:183], v[228:231], v[94:97]
	v_mfma_f32_16x16x32_bf16 v[90:93], v[188:191], v[228:231], v[90:93]
	v_mfma_f32_16x16x32_bf16 v[78:81], v[180:183], v[236:239], v[78:81]
	v_mfma_f32_16x16x32_bf16 v[74:77], v[188:191], v[236:239], v[74:77]
	v_mfma_f32_16x16x32_bf16 v[126:129], v[184:187], v[200:203], v[126:129]
	v_mfma_f32_16x16x32_bf16 v[122:125], v[192:195], v[200:203], v[122:125]
	v_mfma_f32_16x16x32_bf16 v[110:113], v[184:187], v[224:227], v[110:113]
	v_mfma_f32_16x16x32_bf16 v[106:109], v[192:195], v[224:227], v[106:109]
	v_mfma_f32_16x16x32_bf16 v[94:97], v[184:187], v[232:235], v[94:97]
	v_mfma_f32_16x16x32_bf16 v[90:93], v[192:195], v[232:235], v[90:93]
	v_mfma_f32_16x16x32_bf16 v[78:81], v[184:187], v[244:247], v[78:81]
	v_mfma_f32_16x16x32_bf16 v[74:77], v[192:195], v[244:247], v[74:77]
	s_setprio 0
	s_barrier
	s_add_i32 s97, s91, s10
	v_lshl_add_u64 v[146:147], s[80:81], 0, v[2:3]
	s_mov_b32 m0, s97
	ds_read_b128 v[196:199], v154 offset:16384
	ds_read_b128 v[200:203], v154 offset:17408
	ds_read_b128 v[220:223], v154 offset:18432
	ds_read_b128 v[224:227], v154 offset:19456
	ds_read_b128 v[228:231], v154 offset:20480
	ds_read_b128 v[232:235], v154 offset:21504
	ds_read_b128 v[236:239], v154 offset:22528
	ds_read_b128 v[244:247], v154 offset:23552
	global_load_lds_dwordx4 v[146:147], off
	s_add_i32 m0, s97, 0x2000
	v_lshl_add_u64 v[150:151], s[80:81], 0, v[4:5]
	s_add_u32 s80, s80, s96
	s_addc_u32 s81, s81, 0
	s_add_i32 s97, vcc_hi, s10
	global_load_lds_dwordx4 v[150:151], off
	v_lshl_add_u64 v[168:169], s[80:81], 0, v[2:3]
	s_mov_b32 m0, s97
	v_lshl_add_u64 v[172:173], s[80:81], 0, v[4:5]
	global_load_lds_dwordx4 v[168:169], off
	s_add_i32 m0, s97, 0x2000
	v_lshl_add_u64 v[240:241], s[82:83], 0, v[140:141]
	global_load_lds_dwordx4 v[172:173], off
	s_mov_b32 m0, s26
	v_lshl_add_u64 v[248:249], s[82:83], 0, v[138:139]
	global_load_lds_dwordx4 v[240:241], off
	s_mov_b32 m0, s68
	s_nop 0
	global_load_lds_dwordx4 v[248:249], off
	s_waitcnt vmcnt(8)
	s_waitcnt lgkmcnt(0)
	s_barrier
	s_setprio 1
	s_waitcnt lgkmcnt(0)
	v_mfma_f32_16x16x32_bf16 v[70:73], v[156:159], v[196:199], v[70:73]
	v_mfma_f32_16x16x32_bf16 v[66:69], v[164:167], v[196:199], v[66:69]
	v_mfma_f32_16x16x32_bf16 v[54:57], v[156:159], v[220:223], v[54:57]
	v_mfma_f32_16x16x32_bf16 v[50:53], v[164:167], v[220:223], v[50:53]
	v_mfma_f32_16x16x32_bf16 v[38:41], v[156:159], v[228:231], v[38:41]
	v_mfma_f32_16x16x32_bf16 v[34:37], v[164:167], v[228:231], v[34:37]
	v_mfma_f32_16x16x32_bf16 v[22:25], v[156:159], v[236:239], v[22:25]
	v_mfma_f32_16x16x32_bf16 v[18:21], v[164:167], v[236:239], v[18:21]
	v_mfma_f32_16x16x32_bf16 v[70:73], v[160:163], v[200:203], v[70:73]
	v_mfma_f32_16x16x32_bf16 v[66:69], v[176:179], v[200:203], v[66:69]
	v_mfma_f32_16x16x32_bf16 v[54:57], v[160:163], v[224:227], v[54:57]
	v_mfma_f32_16x16x32_bf16 v[50:53], v[176:179], v[224:227], v[50:53]
	v_mfma_f32_16x16x32_bf16 v[38:41], v[160:163], v[232:235], v[38:41]
	v_mfma_f32_16x16x32_bf16 v[34:37], v[176:179], v[232:235], v[34:37]
	v_mfma_f32_16x16x32_bf16 v[22:25], v[160:163], v[244:247], v[22:25]
	v_mfma_f32_16x16x32_bf16 v[18:21], v[176:179], v[244:247], v[18:21]
	s_setprio 0
	s_setprio 1
	v_mfma_f32_16x16x32_bf16 v[62:65], v[180:183], v[196:199], v[62:65]
	v_mfma_f32_16x16x32_bf16 v[58:61], v[188:191], v[196:199], v[58:61]
	v_mfma_f32_16x16x32_bf16 v[46:49], v[180:183], v[220:223], v[46:49]
	v_mfma_f32_16x16x32_bf16 v[42:45], v[188:191], v[220:223], v[42:45]
	v_mfma_f32_16x16x32_bf16 v[30:33], v[180:183], v[228:231], v[30:33]
	v_mfma_f32_16x16x32_bf16 v[26:29], v[188:191], v[228:231], v[26:29]
	v_mfma_f32_16x16x32_bf16 v[14:17], v[180:183], v[236:239], v[14:17]
	v_mfma_f32_16x16x32_bf16 v[10:13], v[188:191], v[236:239], v[10:13]
	v_mfma_f32_16x16x32_bf16 v[62:65], v[184:187], v[200:203], v[62:65]
	v_mfma_f32_16x16x32_bf16 v[58:61], v[192:195], v[200:203], v[58:61]
	v_mfma_f32_16x16x32_bf16 v[46:49], v[184:187], v[224:227], v[46:49]
	v_mfma_f32_16x16x32_bf16 v[42:45], v[192:195], v[224:227], v[42:45]
	v_mfma_f32_16x16x32_bf16 v[30:33], v[184:187], v[232:235], v[30:33]
	v_mfma_f32_16x16x32_bf16 v[26:29], v[192:195], v[232:235], v[26:29]
	v_mfma_f32_16x16x32_bf16 v[14:17], v[184:187], v[244:247], v[14:17]
	v_mfma_f32_16x16x32_bf16 v[10:13], v[192:195], v[244:247], v[10:13]
	s_setprio 0
	s_barrier
; #define PG8_STAGE(bufoff, gbase, voff) do { _Pragma("unroll") for (int _i = 0; _i < 2; ++_i) \
;         __builtin_amdgcn_global_load_lds((const unsigned*)((const char*)(gbase) + (voff)[_i]), (LAS unsigned*)(lds + (bufoff) + ldsw + _i * 8192), 16, 0, 0); } while (0)
; #define PG8_LDA(dst, b, h) do { _Pragma("unroll") for (int m = 0; m < 4; ++m) _Pragma("unroll") for (int k = 0; k < 2; ++k) dst[m][k] = *(const LAS bf16x8*)(lds + PG8_SA(b, h) + aoff + m * 2048 + k * 1024); } while (0)
; #define PG8_LDB(dst, b, h) do { _Pragma("unroll") for (int n = 0; n < 2; ++n) _Pragma("unroll") for (int k = 0; k < 2; ++k) dst[n][k] = *(const LAS bf16x8*)(lds + PG8_SB(b, h) + boff + n * 2048 + k * 1024); } while (0)
; #define PG8_MMA(ai, bj, At, Bt) do { __builtin_amdgcn_s_setprio(1); _Pragma("unroll") for (int m = 0; m < 4; ++m) _Pragma("unroll") for (int n = 0; n < 2; ++n) _Pragma("unroll") for (int k = 0; k < 2; ++k) \
;         acc[ai][bj][m][n] = __builtin_amdgcn_mfma_f32_16x16x32_bf16(Bt[n][k], At[m][k], acc[ai][bj][m][n], 0, 0, 0); __builtin_amdgcn_s_setprio(0); } while (0)
; #define PG8_WAIT_V(n) asm volatile("s_waitcnt vmcnt(" #n ")" ::: "memory")
; #define PG8_WAIT_L(n) asm volatile("s_waitcnt lgkmcnt(" #n ")" ::: "memory")
; #define PG8_BAR __builtin_amdgcn_s_barrier()
; #define PG8_SCHED __builtin_amdgcn_sched_barrier(0)
; template <class Epi, bool ALIGN_EPI = true>
; __device__ __forceinline__ void gemm_phase(LAS unsigned char* lds, const Gemm g, const StaticOrder& S, const Epi& E) {
;     ...
;             PG8_LDB(B0, 1, 0); PG8_LDB(B1, 1, 1); PG8_SCHED; PG8_LDA(At, 1, 0); PG8_STAGE(PG8_SA(0, 1), a2 + hsA, voffA);
;             PG8_WAIT_V(8); PG8_WAIT_L(0); PG8_BAR; PG8_MMA(0, 0, At, B0); PG8_MMA(0, 1, At, B1); PG8_BAR; PG8_SCHED;
	s_add_i32 s97, 0, 0x18000
	v_add_u32_e32 v148, s97, v153
	s_add_i32 vcc_hi, 0, 0x1c000
	ds_read_b128 v[156:159], v148
	ds_read_b128 v[160:163], v148 offset:1024
	ds_read_b128 v[164:167], v148 offset:2048
	ds_read_b128 v[176:179], v148 offset:3072
	v_add_u32_e32 v148, vcc_hi, v153
	ds_read_b128 v[180:183], v148
	ds_read_b128 v[184:187], v148 offset:1024
	ds_read_b128 v[188:191], v148 offset:2048
	ds_read_b128 v[192:195], v148 offset:3072
	s_add_u32 s80, s82, s14
	s_addc_u32 s81, s83, 0
	s_mov_b32 m0, s69
	v_lshl_add_u64 v[250:251], s[80:81], 0, v[140:141]
	ds_read_b128 v[196:199], v154 offset:32768
	ds_read_b128 v[200:203], v154 offset:33792
	ds_read_b128 v[220:223], v154 offset:34816
	ds_read_b128 v[224:227], v154 offset:35840
	ds_read_b128 v[228:231], v154 offset:36864
	ds_read_b128 v[232:235], v154 offset:37888
	ds_read_b128 v[236:239], v154 offset:38912
	ds_read_b128 v[244:247], v154 offset:39936
	global_load_lds_dwordx4 v[250:251], off
	v_lshl_add_u64 v[250:251], s[80:81], 0, v[138:139]
	s_mov_b32 m0, s73
	s_nop 0
	global_load_lds_dwordx4 v[250:251], off
	s_waitcnt vmcnt(8)
	s_waitcnt lgkmcnt(0)
	s_barrier
	s_setprio 1
	s_waitcnt lgkmcnt(0)
	v_mfma_f32_16x16x32_bf16 v[134:137], v[156:159], v[196:199], v[134:137]
	v_mfma_f32_16x16x32_bf16 v[130:133], v[164:167], v[196:199], v[130:133]
	v_mfma_f32_16x16x32_bf16 v[118:121], v[156:159], v[220:223], v[118:121]
	v_mfma_f32_16x16x32_bf16 v[114:117], v[164:167], v[220:223], v[114:117]
	v_mfma_f32_16x16x32_bf16 v[102:105], v[156:159], v[228:231], v[102:105]
	v_mfma_f32_16x16x32_bf16 v[98:101], v[164:167], v[228:231], v[98:101]
	v_mfma_f32_16x16x32_bf16 v[86:89], v[156:159], v[236:239], v[86:89]
	v_mfma_f32_16x16x32_bf16 v[82:85], v[164:167], v[236:239], v[82:85]
	v_mfma_f32_16x16x32_bf16 v[134:137], v[160:163], v[200:203], v[134:137]
	v_mfma_f32_16x16x32_bf16 v[130:133], v[176:179], v[200:203], v[130:133]
	v_mfma_f32_16x16x32_bf16 v[118:121], v[160:163], v[224:227], v[118:121]
	v_mfma_f32_16x16x32_bf16 v[114:117], v[176:179], v[224:227], v[114:117]
	v_mfma_f32_16x16x32_bf16 v[102:105], v[160:163], v[232:235], v[102:105]
	v_mfma_f32_16x16x32_bf16 v[98:101], v[176:179], v[232:235], v[98:101]
	v_mfma_f32_16x16x32_bf16 v[86:89], v[160:163], v[244:247], v[86:89]
	v_mfma_f32_16x16x32_bf16 v[82:85], v[176:179], v[244:247], v[82:85]
	s_setprio 0
	s_setprio 1
	v_mfma_f32_16x16x32_bf16 v[126:129], v[180:183], v[196:199], v[126:129]
	v_mfma_f32_16x16x32_bf16 v[122:125], v[188:191], v[196:199], v[122:125]
	v_mfma_f32_16x16x32_bf16 v[110:113], v[180:183], v[220:223], v[110:113]
	v_mfma_f32_16x16x32_bf16 v[106:109], v[188:191], v[220:223], v[106:109]
	v_mfma_f32_16x16x32_bf16 v[94:97], v[180:183], v[228:231], v[94:97]
	v_mfma_f32_16x16x32_bf16 v[90:93], v[188:191], v[228:231], v[90:93]
	v_mfma_f32_16x16x32_bf16 v[78:81], v[180:183], v[236:239], v[78:81]
	v_mfma_f32_16x16x32_bf16 v[74:77], v[188:191], v[236:239], v[74:77]
	v_mfma_f32_16x16x32_bf16 v[126:129], v[184:187], v[200:203], v[126:129]
	v_mfma_f32_16x16x32_bf16 v[122:125], v[192:195], v[200:203], v[122:125]
	v_mfma_f32_16x16x32_bf16 v[110:113], v[184:187], v[224:227], v[110:113]
	v_mfma_f32_16x16x32_bf16 v[106:109], v[192:195], v[224:227], v[106:109]
	v_mfma_f32_16x16x32_bf16 v[94:97], v[184:187], v[232:235], v[94:97]
	v_mfma_f32_16x16x32_bf16 v[90:93], v[192:195], v[232:235], v[90:93]
	v_mfma_f32_16x16x32_bf16 v[78:81], v[184:187], v[244:247], v[78:81]
	v_mfma_f32_16x16x32_bf16 v[74:77], v[192:195], v[244:247], v[74:77]
	s_setprio 0
	s_barrier
; #define PG8_STAGE(bufoff, gbase, voff) do { _Pragma("unroll") for (int _i = 0; _i < 2; ++_i) \
;         __builtin_amdgcn_global_load_lds((const unsigned*)((const char*)(gbase) + (voff)[_i]), (LAS unsigned*)(lds + (bufoff) + ldsw + _i * 8192), 16, 0, 0); } while (0)
; #define PG8_LDA(dst, b, h) do { _Pragma("unroll") for (int m = 0; m < 4; ++m) _Pragma("unroll") for (int k = 0; k < 2; ++k) dst[m][k] = *(const LAS bf16x8*)(lds + PG8_SA(b, h) + aoff + m * 2048 + k * 1024); } while (0)
; #define PG8_MMA(ai, bj, At, Bt) do { __builtin_amdgcn_s_setprio(1); _Pragma("unroll") for (int m = 0; m < 4; ++m) _Pragma("unroll") for (int n = 0; n < 2; ++n) _Pragma("unroll") for (int k = 0; k < 2; ++k) \
;         acc[ai][bj][m][n] = __builtin_amdgcn_mfma_f32_16x16x32_bf16(Bt[n][k], At[m][k], acc[ai][bj][m][n], 0, 0, 0); __builtin_amdgcn_s_setprio(0); } while (0)
; #define PG8_WAIT_V(n) asm volatile("s_waitcnt vmcnt(" #n ")" ::: "memory")
; #define PG8_WAIT_L(n) asm volatile("s_waitcnt lgkmcnt(" #n ")" ::: "memory")
; #define PG8_BAR __builtin_amdgcn_s_barrier()
; #define PG8_SCHED __builtin_amdgcn_sched_barrier(0)
; template <class Epi, bool ALIGN_EPI = true>
; __device__ __forceinline__ void gemm_phase(LAS unsigned char* lds, const Gemm g, const StaticOrder& S, const Epi& E) {
;     ...
;         for (int t = 0; t < nt; t += 2) {
;             const bool last = (t == nt - 2);
;             const char* a1 = cA + (size_t)(t + 1) * kstep;
;             const char* a2 = last ? nA : cA + (size_t)(t + 2) * kstep; const char* b2 = last ? nB : cB + (size_t)(t + 2) * kstep;
;             const char* a3 = a2 + kstep; const char* b3 = b2 + kstep;
;     ...
;             PG8_LDA(At, 1, 1); PG8_STAGE(PG8_SB(1, 0), b3, voffB); PG8_STAGE(PG8_SB(1, 1), b3 + hsB, voffB); PG8_STAGE(PG8_SA(1, 0), a3, voffA);
;             PG8_WAIT_V(8); PG8_WAIT_L(0); PG8_BAR; PG8_MMA(1, 0, At, B0); PG8_MMA(1, 1, At, B1); PG8_BAR; PG8_SCHED;
	s_add_i32 s80, s97, s10
	v_lshl_add_u64 v[146:147], v[146:147], 0, s[70:71]
	s_mov_b32 m0, s80
	ds_read_b128 v[196:199], v154 offset:49152
	ds_read_b128 v[200:203], v154 offset:50176
	ds_read_b128 v[220:223], v154 offset:51200
	ds_read_b128 v[224:227], v154 offset:52224
	ds_read_b128 v[228:231], v154 offset:53248
	ds_read_b128 v[232:235], v154 offset:54272
	ds_read_b128 v[236:239], v154 offset:55296
	ds_read_b128 v[244:247], v154 offset:56320
	global_load_lds_dwordx4 v[146:147], off
	v_lshl_add_u64 v[146:147], v[150:151], 0, s[70:71]
	s_add_i32 m0, s80, 0x2000
	s_add_i32 s80, vcc_hi, s10
	global_load_lds_dwordx4 v[146:147], off
	v_lshl_add_u64 v[146:147], v[168:169], 0, s[70:71]
	s_mov_b32 m0, s80
	s_nop 0
	global_load_lds_dwordx4 v[146:147], off
	v_lshl_add_u64 v[146:147], v[172:173], 0, s[70:71]
	s_add_i32 m0, s80, 0x2000
	s_nop 0
	global_load_lds_dwordx4 v[146:147], off
	v_lshl_add_u64 v[146:147], v[240:241], 0, s[70:71]
	s_mov_b32 m0, s93
	s_nop 0
	global_load_lds_dwordx4 v[146:147], off
	v_lshl_add_u64 v[146:147], v[248:249], 0, s[70:71]
	s_mov_b32 m0, s74
	s_nop 0
	global_load_lds_dwordx4 v[146:147], off
	s_waitcnt vmcnt(8)
	s_waitcnt lgkmcnt(0)
	s_barrier
	s_setprio 1
	s_waitcnt lgkmcnt(0)
	v_mfma_f32_16x16x32_bf16 v[70:73], v[156:159], v[196:199], v[70:73]
	v_mfma_f32_16x16x32_bf16 v[66:69], v[164:167], v[196:199], v[66:69]
	v_mfma_f32_16x16x32_bf16 v[54:57], v[156:159], v[220:223], v[54:57]
	v_mfma_f32_16x16x32_bf16 v[50:53], v[164:167], v[220:223], v[50:53]
	v_mfma_f32_16x16x32_bf16 v[38:41], v[156:159], v[228:231], v[38:41]
	v_mfma_f32_16x16x32_bf16 v[34:37], v[164:167], v[228:231], v[34:37]
	v_mfma_f32_16x16x32_bf16 v[22:25], v[156:159], v[236:239], v[22:25]
	v_mfma_f32_16x16x32_bf16 v[18:21], v[164:167], v[236:239], v[18:21]
	v_mfma_f32_16x16x32_bf16 v[70:73], v[160:163], v[200:203], v[70:73]
	v_mfma_f32_16x16x32_bf16 v[66:69], v[176:179], v[200:203], v[66:69]
	v_mfma_f32_16x16x32_bf16 v[54:57], v[160:163], v[224:227], v[54:57]
	v_mfma_f32_16x16x32_bf16 v[50:53], v[176:179], v[224:227], v[50:53]
	v_mfma_f32_16x16x32_bf16 v[38:41], v[160:163], v[232:235], v[38:41]
	v_mfma_f32_16x16x32_bf16 v[34:37], v[176:179], v[232:235], v[34:37]
	v_mfma_f32_16x16x32_bf16 v[22:25], v[160:163], v[244:247], v[22:25]
	v_mfma_f32_16x16x32_bf16 v[18:21], v[176:179], v[244:247], v[18:21]
	s_setprio 0
	s_setprio 1
	v_mfma_f32_16x16x32_bf16 v[62:65], v[180:183], v[196:199], v[62:65]
	v_mfma_f32_16x16x32_bf16 v[58:61], v[188:191], v[196:199], v[58:61]
	v_mfma_f32_16x16x32_bf16 v[46:49], v[180:183], v[220:223], v[46:49]
	v_mfma_f32_16x16x32_bf16 v[42:45], v[188:191], v[220:223], v[42:45]
	v_mfma_f32_16x16x32_bf16 v[30:33], v[180:183], v[228:231], v[30:33]
	v_mfma_f32_16x16x32_bf16 v[26:29], v[188:191], v[228:231], v[26:29]
	v_mfma_f32_16x16x32_bf16 v[14:17], v[180:183], v[236:239], v[14:17]
	v_mfma_f32_16x16x32_bf16 v[10:13], v[188:191], v[236:239], v[10:13]
	v_mfma_f32_16x16x32_bf16 v[62:65], v[184:187], v[200:203], v[62:65]
	v_mfma_f32_16x16x32_bf16 v[58:61], v[192:195], v[200:203], v[58:61]
	v_mfma_f32_16x16x32_bf16 v[46:49], v[184:187], v[224:227], v[46:49]
	v_mfma_f32_16x16x32_bf16 v[42:45], v[192:195], v[224:227], v[42:45]
	v_mfma_f32_16x16x32_bf16 v[30:33], v[184:187], v[232:235], v[30:33]
	v_mfma_f32_16x16x32_bf16 v[26:29], v[192:195], v[232:235], v[26:29]
	v_mfma_f32_16x16x32_bf16 v[14:17], v[184:187], v[244:247], v[14:17]
	v_mfma_f32_16x16x32_bf16 v[10:13], v[192:195], v[244:247], v[10:13]
	s_setprio 0
	s_add_u32 s0, s0, 0x100
	s_addc_u32 s1, s1, 0
	s_add_u32 s86, s86, 0x100
	s_addc_u32 s87, s87, 0
	s_cmp_ge_u32 vcc_lo, s95
	s_mov_b32 s82, vcc_lo
	s_cbranch_scc1 .Lrot_exit_297
	s_add_i32 vcc_lo, s82, 2
	s_add_u32 s80, s0, 0x80
	s_addc_u32 s81, s1, 0
	s_cmp_eq_u32 s72, s82
	s_cselect_b32 s83, s25, s81
	s_cselect_b32 s82, s24, s80
	v_add_u32_e32 v146, s91, v153
	s_cselect_b32 s81, s85, s87
	s_cselect_b32 s80, s84, s86
	s_add_i32 vcc_hi, 0, 0x14000
	s_barrier
	s_branch .LBB0_297
.Lrot_exit_297:
	s_barrier
	s_and_b64 vcc, exec, s[22:23]
	s_cbranch_vccz .LBB0_300
	s_barrier

; #define PG8_STAGE(bufoff, gbase, voff) do { _Pragma("unroll") for (int _i = 0; _i < 2; ++_i) \
;         __builtin_amdgcn_global_load_lds((const unsigned*)((const char*)(gbase) + (voff)[_i]), (LAS unsigned*)(lds + (bufoff) + ldsw + _i * 8192), 16, 0, 0); } while (0)
; #define PG8_LDA(dst, b, h) do { _Pragma("unroll") for (int m = 0; m < 4; ++m) _Pragma("unroll") for (int k = 0; k < 2; ++k) dst[m][k] = *(const LAS bf16x8*)(lds + PG8_SA(b, h) + aoff + m * 2048 + k * 1024); } while (0)
; #define PG8_LDB(dst, b, h) do { _Pragma("unroll") for (int n = 0; n < 2; ++n) _Pragma("unroll") for (int k = 0; k < 2; ++k) dst[n][k] = *(const LAS bf16x8*)(lds + PG8_SB(b, h) + boff + n * 2048 + k * 1024); } while (0)
; #define PG8_MMA(ai, bj, At, Bt) do { __builtin_amdgcn_s_setprio(1); _Pragma("unroll") for (int m = 0; m < 4; ++m) _Pragma("unroll") for (int n = 0; n < 2; ++n) _Pragma("unroll") for (int k = 0; k < 2; ++k) \
;         acc[ai][bj][m][n] = __builtin_amdgcn_mfma_f32_16x16x32_bf16(Bt[n][k], At[m][k], acc[ai][bj][m][n], 0, 0, 0); __builtin_amdgcn_s_setprio(0); } while (0)
; #define PG8_WAIT_V(n) asm volatile("s_waitcnt vmcnt(" #n ")" ::: "memory")
; #define PG8_WAIT_L(n) asm volatile("s_waitcnt lgkmcnt(" #n ")" ::: "memory")
; #define PG8_BAR __builtin_amdgcn_s_barrier()
; template <class Epi, bool ALIGN_EPI = true>
; __device__ __forceinline__ void gemm_phase(LAS unsigned char* lds, const Gemm g, const StaticOrder& S, const Epi& E) {
;     ...
;         for (int t = 0; t < nt; t += 2) {
;             const bool last = (t == nt - 2);
;             const char* a1 = cA + (size_t)(t + 1) * kstep;
;             const char* a2 = last ? nA : cA + (size_t)(t + 2) * kstep; const char* b2 = last ? nB : cB + (size_t)(t + 2) * kstep;
;             const char* a3 = a2 + kstep; const char* b3 = b2 + kstep;
;             PG8_LDB(B0, 0, 0); PG8_LDB(B1, 0, 1); PG8_SCHED; PG8_LDA(At, 0, 0); PG8_STAGE(PG8_SA(1, 1), a1 + hsA, voffA);
;             PG8_WAIT_V(8); PG8_WAIT_L(0); PG8_BAR; PG8_MMA(0, 0, At, B0); PG8_MMA(0, 1, At, B1); PG8_BAR; PG8_SCHED;
;     ...
;         for (int a = 0; a < 2; ++a)
; #pragma unroll
;             for (int b = 0; b < 2; ++b)
; #pragma unroll
;                 for (int m = 0; m < 4; ++m)
; #pragma unroll
;                     for (int n = 0; n < 2; ++n) acc[a][b][m][n] = (f32x4){0.f, 0.f, 0.f, 0.f};
;         cur = nxt; cA = nA; cB = nB; ++ui;
.LBB0_327:
	s_add_u32 s0, s84, 0x80
	s_addc_u32 s1, s85, 0
	s_add_u32 s3, s82, 0x100
	v_mov_b32_e32 v10, 0
	s_addc_u32 s10, s83, 0
	s_mov_b32 s11, 0
	v_mov_b32_e32 v11, v10
	v_mov_b32_e32 v12, v10
	v_mov_b32_e32 v13, v10
	v_mov_b32_e32 v14, v10
	v_mov_b32_e32 v15, v10
	v_mov_b32_e32 v16, v10
	v_mov_b32_e32 v17, v10
	v_mov_b32_e32 v26, v10
	v_mov_b32_e32 v27, v10
	v_mov_b32_e32 v28, v10
	v_mov_b32_e32 v29, v10
	v_mov_b32_e32 v30, v10
	v_mov_b32_e32 v31, v10
	v_mov_b32_e32 v32, v10
	v_mov_b32_e32 v33, v10
	v_mov_b32_e32 v38, v10
	v_mov_b32_e32 v39, v10
	v_mov_b32_e32 v40, v10
	v_mov_b32_e32 v41, v10
	v_mov_b32_e32 v46, v10
	v_mov_b32_e32 v47, v10
	v_mov_b32_e32 v48, v10
	v_mov_b32_e32 v49, v10
	v_mov_b32_e32 v54, v10
	v_mov_b32_e32 v55, v10
	v_mov_b32_e32 v56, v10
	v_mov_b32_e32 v57, v10
	v_mov_b32_e32 v62, v10
	v_mov_b32_e32 v63, v10
	v_mov_b32_e32 v64, v10
	v_mov_b32_e32 v65, v10
	v_mov_b32_e32 v18, v10
	v_mov_b32_e32 v19, v10
	v_mov_b32_e32 v20, v10
	v_mov_b32_e32 v21, v10
	v_mov_b32_e32 v22, v10
	v_mov_b32_e32 v23, v10
	v_mov_b32_e32 v24, v10
	v_mov_b32_e32 v25, v10
	v_mov_b32_e32 v34, v10
	v_mov_b32_e32 v35, v10
	v_mov_b32_e32 v36, v10
	v_mov_b32_e32 v37, v10
	v_mov_b32_e32 v42, v10
	v_mov_b32_e32 v43, v10
	v_mov_b32_e32 v44, v10
	v_mov_b32_e32 v45, v10
	v_mov_b32_e32 v50, v10
	v_mov_b32_e32 v51, v10
	v_mov_b32_e32 v52, v10
	v_mov_b32_e32 v53, v10
	v_mov_b32_e32 v58, v10
	v_mov_b32_e32 v59, v10
	v_mov_b32_e32 v60, v10
	v_mov_b32_e32 v61, v10
	v_mov_b32_e32 v66, v10
	v_mov_b32_e32 v67, v10
	v_mov_b32_e32 v68, v10
	v_mov_b32_e32 v69, v10
	v_mov_b32_e32 v70, v10
	v_mov_b32_e32 v71, v10
	v_mov_b32_e32 v72, v10
	v_mov_b32_e32 v73, v10
	v_mov_b32_e32 v74, v10
	v_mov_b32_e32 v75, v10
	v_mov_b32_e32 v76, v10
	v_mov_b32_e32 v77, v10
	v_mov_b32_e32 v78, v10
	v_mov_b32_e32 v79, v10
	v_mov_b32_e32 v80, v10
	v_mov_b32_e32 v81, v10
	v_mov_b32_e32 v90, v10
	v_mov_b32_e32 v91, v10
	v_mov_b32_e32 v92, v10
	v_mov_b32_e32 v93, v10
	v_mov_b32_e32 v94, v10
	v_mov_b32_e32 v95, v10
	v_mov_b32_e32 v96, v10
	v_mov_b32_e32 v97, v10
	v_mov_b32_e32 v102, v10
	v_mov_b32_e32 v103, v10
	v_mov_b32_e32 v104, v10
	v_mov_b32_e32 v105, v10
	v_mov_b32_e32 v110, v10
	v_mov_b32_e32 v111, v10
	v_mov_b32_e32 v112, v10
	v_mov_b32_e32 v113, v10
	v_mov_b32_e32 v118, v10
	v_mov_b32_e32 v119, v10
	v_mov_b32_e32 v120, v10
	v_mov_b32_e32 v121, v10
	v_mov_b32_e32 v126, v10
	v_mov_b32_e32 v127, v10
	v_mov_b32_e32 v128, v10
	v_mov_b32_e32 v129, v10
	v_mov_b32_e32 v82, v10
	v_mov_b32_e32 v83, v10
	v_mov_b32_e32 v84, v10
	v_mov_b32_e32 v85, v10
	v_mov_b32_e32 v86, v10
	v_mov_b32_e32 v87, v10
	v_mov_b32_e32 v88, v10
	v_mov_b32_e32 v89, v10
	v_mov_b32_e32 v98, v10
	v_mov_b32_e32 v99, v10
	v_mov_b32_e32 v100, v10
	v_mov_b32_e32 v101, v10
	v_mov_b32_e32 v106, v10
	v_mov_b32_e32 v107, v10
	v_mov_b32_e32 v108, v10
	v_mov_b32_e32 v109, v10
	v_mov_b32_e32 v114, v10
	v_mov_b32_e32 v115, v10
	v_mov_b32_e32 v116, v10
	v_mov_b32_e32 v117, v10
	v_mov_b32_e32 v122, v10
	v_mov_b32_e32 v123, v10
	v_mov_b32_e32 v124, v10
	v_mov_b32_e32 v125, v10
	v_mov_b32_e32 v130, v10
	v_mov_b32_e32 v131, v10
	v_mov_b32_e32 v132, v10
	v_mov_b32_e32 v133, v10
	v_mov_b32_e32 v134, v10
	v_mov_b32_e32 v135, v10
	v_mov_b32_e32 v136, v10
	v_mov_b32_e32 v137, v10
	s_add_i32 s26, s11, 2
	s_add_u32 s69, s0, 0x80
	s_addc_u32 s74, s1, 0
	s_cmp_eq_u32 s72, s11
	s_cselect_b32 s83, s23, s74
	s_cselect_b32 s82, s22, s69
	v_add_u32_e32 v2, s91, v176
	s_cselect_b32 s75, s25, s10
	s_cselect_b32 s74, s24, s3
	s_add_i32 s11, 0, 0x14000
.LBB0_328:
	ds_read_b128 v[138:141], v2
	ds_read_b128 v[142:145], v2 offset:1024
	ds_read_b128 v[146:149], v2 offset:2048
	ds_read_b128 v[150:153], v2 offset:3072
	v_add_u32_e32 v2, s11, v176
	ds_read_b128 v[164:167], v2
	ds_read_b128 v[178:181], v2 offset:1024
	ds_read_b128 v[182:185], v2 offset:2048
	ds_read_b128 v[186:189], v2 offset:3072
	v_lshl_add_u64 v[202:203], s[0:1], 0, v[160:161]
	s_add_i32 m0, s86, 0xc000
	ds_read_b128 v[190:193], v1
	ds_read_b128 v[194:197], v1 offset:1024
	ds_read_b128 v[198:201], v1 offset:2048
	ds_read_b128 v[220:223], v1 offset:3072
	ds_read_b128 v[224:227], v1 offset:4096
	ds_read_b128 v[228:231], v1 offset:5120
	ds_read_b128 v[232:235], v1 offset:6144
	ds_read_b128 v[236:239], v1 offset:7168
	global_load_lds_dwordx4 v[202:203], off
	v_lshl_add_u64 v[202:203], s[0:1], 0, v[162:163]
	s_add_i32 m0, s86, 0xe000
	s_nop 0
	global_load_lds_dwordx4 v[202:203], off
	s_waitcnt vmcnt(8)
	s_waitcnt lgkmcnt(0)
	s_barrier
; #define PG8_STAGE(bufoff, gbase, voff) do { _Pragma("unroll") for (int _i = 0; _i < 2; ++_i) \
;         __builtin_amdgcn_global_load_lds((const unsigned*)((const char*)(gbase) + (voff)[_i]), (LAS unsigned*)(lds + (bufoff) + ldsw + _i * 8192), 16, 0, 0); } while (0)
; #define PG8_LDA(dst, b, h) do { _Pragma("unroll") for (int m = 0; m < 4; ++m) _Pragma("unroll") for (int k = 0; k < 2; ++k) dst[m][k] = *(const LAS bf16x8*)(lds + PG8_SA(b, h) + aoff + m * 2048 + k * 1024); } while (0)
; #define PG8_MMA(ai, bj, At, Bt) do { __builtin_amdgcn_s_setprio(1); _Pragma("unroll") for (int m = 0; m < 4; ++m) _Pragma("unroll") for (int n = 0; n < 2; ++n) _Pragma("unroll") for (int k = 0; k < 2; ++k) \
;         acc[ai][bj][m][n] = __builtin_amdgcn_mfma_f32_16x16x32_bf16(Bt[n][k], At[m][k], acc[ai][bj][m][n], 0, 0, 0); __builtin_amdgcn_s_setprio(0); } while (0)
; #define PG8_WAIT_V(n) asm volatile("s_waitcnt vmcnt(" #n ")" ::: "memory")
; #define PG8_WAIT_L(n) asm volatile("s_waitcnt lgkmcnt(" #n ")" ::: "memory")
; #define PG8_BAR __builtin_amdgcn_s_barrier()
; #define PG8_SCHED __builtin_amdgcn_sched_barrier(0)
; template <class Epi, bool ALIGN_EPI = true>
; __device__ __forceinline__ void gemm_phase(LAS unsigned char* lds, const Gemm g, const StaticOrder& S, const Epi& E) {
;     ...
;             PG8_WAIT_V(8); PG8_WAIT_L(0); PG8_BAR; PG8_MMA(0, 0, At, B0); PG8_MMA(0, 1, At, B1); PG8_BAR; PG8_SCHED;
;             PG8_LDA(At, 0, 1); PG8_STAGE(PG8_SB(0, 0), b2, voffB); PG8_STAGE(PG8_SB(0, 1), b2 + hsB, voffB); PG8_STAGE(PG8_SA(0, 0), a2, voffA);
;             PG8_WAIT_V(8); PG8_WAIT_L(0); PG8_BAR; PG8_MMA(1, 0, At, B0); PG8_MMA(1, 1, At, B1); PG8_BAR; PG8_SCHED;
	s_setprio 1
	s_waitcnt lgkmcnt(0)
	v_mfma_f32_16x16x32_bf16 v[134:137], v[138:141], v[190:193], v[134:137]
	v_mfma_f32_16x16x32_bf16 v[130:133], v[146:149], v[190:193], v[130:133]
	v_mfma_f32_16x16x32_bf16 v[122:125], v[138:141], v[198:201], v[122:125]
	v_mfma_f32_16x16x32_bf16 v[114:117], v[146:149], v[198:201], v[114:117]
	v_mfma_f32_16x16x32_bf16 v[106:109], v[138:141], v[224:227], v[106:109]
	v_mfma_f32_16x16x32_bf16 v[98:101], v[146:149], v[224:227], v[98:101]
	v_mfma_f32_16x16x32_bf16 v[86:89], v[138:141], v[232:235], v[86:89]
	v_mfma_f32_16x16x32_bf16 v[82:85], v[146:149], v[232:235], v[82:85]
	v_mfma_f32_16x16x32_bf16 v[134:137], v[142:145], v[194:197], v[134:137]
	v_mfma_f32_16x16x32_bf16 v[130:133], v[150:153], v[194:197], v[130:133]
	v_mfma_f32_16x16x32_bf16 v[122:125], v[142:145], v[220:223], v[122:125]
	v_mfma_f32_16x16x32_bf16 v[114:117], v[150:153], v[220:223], v[114:117]
	v_mfma_f32_16x16x32_bf16 v[106:109], v[142:145], v[228:231], v[106:109]
	v_mfma_f32_16x16x32_bf16 v[98:101], v[150:153], v[228:231], v[98:101]
	v_mfma_f32_16x16x32_bf16 v[86:89], v[142:145], v[236:239], v[86:89]
	v_mfma_f32_16x16x32_bf16 v[82:85], v[150:153], v[236:239], v[82:85]
	s_setprio 0
	s_setprio 1
	v_mfma_f32_16x16x32_bf16 v[126:129], v[164:167], v[190:193], v[126:129]
	v_mfma_f32_16x16x32_bf16 v[118:121], v[182:185], v[190:193], v[118:121]
	v_mfma_f32_16x16x32_bf16 v[110:113], v[164:167], v[198:201], v[110:113]
	v_mfma_f32_16x16x32_bf16 v[102:105], v[182:185], v[198:201], v[102:105]
	v_mfma_f32_16x16x32_bf16 v[94:97], v[164:167], v[224:227], v[94:97]
	v_mfma_f32_16x16x32_bf16 v[90:93], v[182:185], v[224:227], v[90:93]
	v_mfma_f32_16x16x32_bf16 v[78:81], v[164:167], v[232:235], v[78:81]
	v_mfma_f32_16x16x32_bf16 v[74:77], v[182:185], v[232:235], v[74:77]
	v_mfma_f32_16x16x32_bf16 v[126:129], v[178:181], v[194:197], v[126:129]
	v_mfma_f32_16x16x32_bf16 v[118:121], v[186:189], v[194:197], v[118:121]
	v_mfma_f32_16x16x32_bf16 v[110:113], v[178:181], v[220:223], v[110:113]
	v_mfma_f32_16x16x32_bf16 v[102:105], v[186:189], v[220:223], v[102:105]
	v_mfma_f32_16x16x32_bf16 v[94:97], v[178:181], v[228:231], v[94:97]
	v_mfma_f32_16x16x32_bf16 v[90:93], v[186:189], v[228:231], v[90:93]
	v_mfma_f32_16x16x32_bf16 v[78:81], v[178:181], v[236:239], v[78:81]
	v_mfma_f32_16x16x32_bf16 v[74:77], v[186:189], v[236:239], v[74:77]
	s_setprio 0
	s_barrier
	s_add_i32 s69, s91, s73
	v_lshl_add_u64 v[202:203], s[74:75], 0, v[154:155]
	s_mov_b32 m0, s69
	ds_read_b128 v[190:193], v1 offset:16384
	ds_read_b128 v[194:197], v1 offset:17408
	ds_read_b128 v[198:201], v1 offset:18432
	ds_read_b128 v[220:223], v1 offset:19456
	ds_read_b128 v[224:227], v1 offset:20480
	ds_read_b128 v[228:231], v1 offset:21504
	ds_read_b128 v[232:235], v1 offset:22528
	ds_read_b128 v[236:239], v1 offset:23552
	global_load_lds_dwordx4 v[202:203], off
	s_add_i32 m0, s69, 0x2000
	v_lshl_add_u64 v[240:241], s[74:75], 0, v[158:159]
	s_add_u32 s74, s74, s96
	s_addc_u32 s75, s75, 0
	s_add_i32 s11, s11, s73
	global_load_lds_dwordx4 v[240:241], off
	v_lshl_add_u64 v[244:245], s[74:75], 0, v[154:155]
	s_mov_b32 m0, s11
	v_lshl_add_u64 v[246:247], s[74:75], 0, v[158:159]
	global_load_lds_dwordx4 v[244:245], off
	s_add_i32 m0, s11, 0x2000
	v_lshl_add_u64 v[248:249], s[82:83], 0, v[4:5]
	global_load_lds_dwordx4 v[246:247], off
	s_mov_b32 m0, s86
	v_lshl_add_u64 v[250:251], s[82:83], 0, v[156:157]
	global_load_lds_dwordx4 v[248:249], off
	s_mov_b32 m0, s87
	s_nop 0
	global_load_lds_dwordx4 v[250:251], off
	s_waitcnt vmcnt(8)
	s_waitcnt lgkmcnt(0)
	s_barrier
	s_setprio 1
	s_waitcnt lgkmcnt(0)
	v_mfma_f32_16x16x32_bf16 v[70:73], v[138:141], v[190:193], v[70:73]
	v_mfma_f32_16x16x32_bf16 v[66:69], v[146:149], v[190:193], v[66:69]
	v_mfma_f32_16x16x32_bf16 v[58:61], v[138:141], v[198:201], v[58:61]
	v_mfma_f32_16x16x32_bf16 v[50:53], v[146:149], v[198:201], v[50:53]
	v_mfma_f32_16x16x32_bf16 v[42:45], v[138:141], v[224:227], v[42:45]
	v_mfma_f32_16x16x32_bf16 v[34:37], v[146:149], v[224:227], v[34:37]
	v_mfma_f32_16x16x32_bf16 v[22:25], v[138:141], v[232:235], v[22:25]
	v_mfma_f32_16x16x32_bf16 v[18:21], v[146:149], v[232:235], v[18:21]
	v_mfma_f32_16x16x32_bf16 v[70:73], v[142:145], v[194:197], v[70:73]
	v_mfma_f32_16x16x32_bf16 v[66:69], v[150:153], v[194:197], v[66:69]
	v_mfma_f32_16x16x32_bf16 v[58:61], v[142:145], v[220:223], v[58:61]
	v_mfma_f32_16x16x32_bf16 v[50:53], v[150:153], v[220:223], v[50:53]
	v_mfma_f32_16x16x32_bf16 v[42:45], v[142:145], v[228:231], v[42:45]
	v_mfma_f32_16x16x32_bf16 v[34:37], v[150:153], v[228:231], v[34:37]
	v_mfma_f32_16x16x32_bf16 v[22:25], v[142:145], v[236:239], v[22:25]
	v_mfma_f32_16x16x32_bf16 v[18:21], v[150:153], v[236:239], v[18:21]
	s_setprio 0
	s_setprio 1
	v_mfma_f32_16x16x32_bf16 v[62:65], v[164:167], v[190:193], v[62:65]
	v_mfma_f32_16x16x32_bf16 v[54:57], v[182:185], v[190:193], v[54:57]
	v_mfma_f32_16x16x32_bf16 v[46:49], v[164:167], v[198:201], v[46:49]
	v_mfma_f32_16x16x32_bf16 v[38:41], v[182:185], v[198:201], v[38:41]
	v_mfma_f32_16x16x32_bf16 v[30:33], v[164:167], v[224:227], v[30:33]
	v_mfma_f32_16x16x32_bf16 v[26:29], v[182:185], v[224:227], v[26:29]
	v_mfma_f32_16x16x32_bf16 v[14:17], v[164:167], v[232:235], v[14:17]
	v_mfma_f32_16x16x32_bf16 v[10:13], v[182:185], v[232:235], v[10:13]
	v_mfma_f32_16x16x32_bf16 v[62:65], v[178:181], v[194:197], v[62:65]
	v_mfma_f32_16x16x32_bf16 v[54:57], v[186:189], v[194:197], v[54:57]
	v_mfma_f32_16x16x32_bf16 v[46:49], v[178:181], v[220:223], v[46:49]
	v_mfma_f32_16x16x32_bf16 v[38:41], v[186:189], v[220:223], v[38:41]
	v_mfma_f32_16x16x32_bf16 v[30:33], v[178:181], v[228:231], v[30:33]
	v_mfma_f32_16x16x32_bf16 v[26:29], v[186:189], v[228:231], v[26:29]
	v_mfma_f32_16x16x32_bf16 v[14:17], v[178:181], v[236:239], v[14:17]
	v_mfma_f32_16x16x32_bf16 v[10:13], v[186:189], v[236:239], v[10:13]
	s_setprio 0
	s_barrier
; #define PG8_STAGE(bufoff, gbase, voff) do { _Pragma("unroll") for (int _i = 0; _i < 2; ++_i) \
;         __builtin_amdgcn_global_load_lds((const unsigned*)((const char*)(gbase) + (voff)[_i]), (LAS unsigned*)(lds + (bufoff) + ldsw + _i * 8192), 16, 0, 0); } while (0)
; #define PG8_LDA(dst, b, h) do { _Pragma("unroll") for (int m = 0; m < 4; ++m) _Pragma("unroll") for (int k = 0; k < 2; ++k) dst[m][k] = *(const LAS bf16x8*)(lds + PG8_SA(b, h) + aoff + m * 2048 + k * 1024); } while (0)
; #define PG8_LDB(dst, b, h) do { _Pragma("unroll") for (int n = 0; n < 2; ++n) _Pragma("unroll") for (int k = 0; k < 2; ++k) dst[n][k] = *(const LAS bf16x8*)(lds + PG8_SB(b, h) + boff + n * 2048 + k * 1024); } while (0)
; #define PG8_MMA(ai, bj, At, Bt) do { __builtin_amdgcn_s_setprio(1); _Pragma("unroll") for (int m = 0; m < 4; ++m) _Pragma("unroll") for (int n = 0; n < 2; ++n) _Pragma("unroll") for (int k = 0; k < 2; ++k) \
;         acc[ai][bj][m][n] = __builtin_amdgcn_mfma_f32_16x16x32_bf16(Bt[n][k], At[m][k], acc[ai][bj][m][n], 0, 0, 0); __builtin_amdgcn_s_setprio(0); } while (0)
; #define PG8_WAIT_V(n) asm volatile("s_waitcnt vmcnt(" #n ")" ::: "memory")
; #define PG8_WAIT_L(n) asm volatile("s_waitcnt lgkmcnt(" #n ")" ::: "memory")
; #define PG8_BAR __builtin_amdgcn_s_barrier()
; #define PG8_SCHED __builtin_amdgcn_sched_barrier(0)
; template <class Epi, bool ALIGN_EPI = true>
; __device__ __forceinline__ void gemm_phase(LAS unsigned char* lds, const Gemm g, const StaticOrder& S, const Epi& E) {
;     ...
;             PG8_LDB(B0, 1, 0); PG8_LDB(B1, 1, 1); PG8_SCHED; PG8_LDA(At, 1, 0); PG8_STAGE(PG8_SA(0, 1), a2 + hsA, voffA);
;             PG8_WAIT_V(8); PG8_WAIT_L(0); PG8_BAR; PG8_MMA(0, 0, At, B0); PG8_MMA(0, 1, At, B1); PG8_BAR; PG8_SCHED;
	s_add_i32 s11, 0, 0x18000
	v_add_u32_e32 v2, s11, v176
	s_add_i32 s69, 0, 0x1c000
	ds_read_b128 v[138:141], v2
	ds_read_b128 v[142:145], v2 offset:1024
	ds_read_b128 v[146:149], v2 offset:2048
	ds_read_b128 v[150:153], v2 offset:3072
	v_add_u32_e32 v2, s69, v176
	ds_read_b128 v[164:167], v2
	ds_read_b128 v[178:181], v2 offset:1024
	ds_read_b128 v[182:185], v2 offset:2048
	ds_read_b128 v[186:189], v2 offset:3072
	s_add_u32 s74, s82, s14
	s_addc_u32 s75, s83, 0
	s_mov_b32 m0, s88
	v_lshl_add_u64 v[172:173], s[74:75], 0, v[4:5]
	ds_read_b128 v[190:193], v1 offset:32768
	ds_read_b128 v[194:197], v1 offset:33792
	ds_read_b128 v[198:201], v1 offset:34816
	ds_read_b128 v[220:223], v1 offset:35840
	ds_read_b128 v[224:227], v1 offset:36864
	ds_read_b128 v[228:231], v1 offset:37888
	ds_read_b128 v[232:235], v1 offset:38912
	ds_read_b128 v[236:239], v1 offset:39936
	global_load_lds_dwordx4 v[172:173], off
	v_lshl_add_u64 v[172:173], s[74:75], 0, v[156:157]
	s_mov_b32 m0, s89
	s_nop 0
	global_load_lds_dwordx4 v[172:173], off
	s_waitcnt vmcnt(8)
	s_waitcnt lgkmcnt(0)
	s_barrier
	s_setprio 1
	s_waitcnt lgkmcnt(0)
	v_mfma_f32_16x16x32_bf16 v[134:137], v[138:141], v[190:193], v[134:137]
	v_mfma_f32_16x16x32_bf16 v[130:133], v[146:149], v[190:193], v[130:133]
	v_mfma_f32_16x16x32_bf16 v[122:125], v[138:141], v[198:201], v[122:125]
	v_mfma_f32_16x16x32_bf16 v[114:117], v[146:149], v[198:201], v[114:117]
	v_mfma_f32_16x16x32_bf16 v[106:109], v[138:141], v[224:227], v[106:109]
	v_mfma_f32_16x16x32_bf16 v[98:101], v[146:149], v[224:227], v[98:101]
	v_mfma_f32_16x16x32_bf16 v[86:89], v[138:141], v[232:235], v[86:89]
	v_mfma_f32_16x16x32_bf16 v[82:85], v[146:149], v[232:235], v[82:85]
	v_mfma_f32_16x16x32_bf16 v[134:137], v[142:145], v[194:197], v[134:137]
	v_mfma_f32_16x16x32_bf16 v[130:133], v[150:153], v[194:197], v[130:133]
	v_mfma_f32_16x16x32_bf16 v[122:125], v[142:145], v[220:223], v[122:125]
	v_mfma_f32_16x16x32_bf16 v[114:117], v[150:153], v[220:223], v[114:117]
	v_mfma_f32_16x16x32_bf16 v[106:109], v[142:145], v[228:231], v[106:109]
	v_mfma_f32_16x16x32_bf16 v[98:101], v[150:153], v[228:231], v[98:101]
	v_mfma_f32_16x16x32_bf16 v[86:89], v[142:145], v[236:239], v[86:89]
	v_mfma_f32_16x16x32_bf16 v[82:85], v[150:153], v[236:239], v[82:85]
	s_setprio 0
	s_setprio 1
	v_mfma_f32_16x16x32_bf16 v[126:129], v[164:167], v[190:193], v[126:129]
	v_mfma_f32_16x16x32_bf16 v[118:121], v[182:185], v[190:193], v[118:121]
	v_mfma_f32_16x16x32_bf16 v[110:113], v[164:167], v[198:201], v[110:113]
	v_mfma_f32_16x16x32_bf16 v[102:105], v[182:185], v[198:201], v[102:105]
	v_mfma_f32_16x16x32_bf16 v[94:97], v[164:167], v[224:227], v[94:97]
	v_mfma_f32_16x16x32_bf16 v[90:93], v[182:185], v[224:227], v[90:93]
	v_mfma_f32_16x16x32_bf16 v[78:81], v[164:167], v[232:235], v[78:81]
	v_mfma_f32_16x16x32_bf16 v[74:77], v[182:185], v[232:235], v[74:77]
	v_mfma_f32_16x16x32_bf16 v[126:129], v[178:181], v[194:197], v[126:129]
	v_mfma_f32_16x16x32_bf16 v[118:121], v[186:189], v[194:197], v[118:121]
	v_mfma_f32_16x16x32_bf16 v[110:113], v[178:181], v[220:223], v[110:113]
	v_mfma_f32_16x16x32_bf16 v[102:105], v[186:189], v[220:223], v[102:105]
	v_mfma_f32_16x16x32_bf16 v[94:97], v[178:181], v[228:231], v[94:97]
	v_mfma_f32_16x16x32_bf16 v[90:93], v[186:189], v[228:231], v[90:93]
	v_mfma_f32_16x16x32_bf16 v[78:81], v[178:181], v[236:239], v[78:81]
	v_mfma_f32_16x16x32_bf16 v[74:77], v[186:189], v[236:239], v[74:77]
	s_setprio 0
	s_barrier
; #define PG8_STAGE(bufoff, gbase, voff) do { _Pragma("unroll") for (int _i = 0; _i < 2; ++_i) \
;         __builtin_amdgcn_global_load_lds((const unsigned*)((const char*)(gbase) + (voff)[_i]), (LAS unsigned*)(lds + (bufoff) + ldsw + _i * 8192), 16, 0, 0); } while (0)
; #define PG8_LDA(dst, b, h) do { _Pragma("unroll") for (int m = 0; m < 4; ++m) _Pragma("unroll") for (int k = 0; k < 2; ++k) dst[m][k] = *(const LAS bf16x8*)(lds + PG8_SA(b, h) + aoff + m * 2048 + k * 1024); } while (0)
; #define PG8_MMA(ai, bj, At, Bt) do { __builtin_amdgcn_s_setprio(1); _Pragma("unroll") for (int m = 0; m < 4; ++m) _Pragma("unroll") for (int n = 0; n < 2; ++n) _Pragma("unroll") for (int k = 0; k < 2; ++k) \
;         acc[ai][bj][m][n] = __builtin_amdgcn_mfma_f32_16x16x32_bf16(Bt[n][k], At[m][k], acc[ai][bj][m][n], 0, 0, 0); __builtin_amdgcn_s_setprio(0); } while (0)
; #define PG8_WAIT_V(n) asm volatile("s_waitcnt vmcnt(" #n ")" ::: "memory")
; #define PG8_WAIT_L(n) asm volatile("s_waitcnt lgkmcnt(" #n ")" ::: "memory")
; #define PG8_BAR __builtin_amdgcn_s_barrier()
; #define PG8_SCHED __builtin_amdgcn_sched_barrier(0)
; template <class Epi, bool ALIGN_EPI = true>
; __device__ __forceinline__ void gemm_phase(LAS unsigned char* lds, const Gemm g, const StaticOrder& S, const Epi& E) {
;     ...
;         for (int t = 0; t < nt; t += 2) {
;             const bool last = (t == nt - 2);
;             const char* a1 = cA + (size_t)(t + 1) * kstep;
;             const char* a2 = last ? nA : cA + (size_t)(t + 2) * kstep; const char* b2 = last ? nB : cB + (size_t)(t + 2) * kstep;
;             const char* a3 = a2 + kstep; const char* b3 = b2 + kstep;
;     ...
;             PG8_LDA(At, 1, 1); PG8_STAGE(PG8_SB(1, 0), b3, voffB); PG8_STAGE(PG8_SB(1, 1), b3 + hsB, voffB); PG8_STAGE(PG8_SA(1, 0), a3, voffA);
;             PG8_WAIT_V(8); PG8_WAIT_L(0); PG8_BAR; PG8_MMA(1, 0, At, B0); PG8_MMA(1, 1, At, B1); PG8_BAR; PG8_SCHED;
	s_add_i32 s11, s11, s73
	v_lshl_add_u64 v[172:173], v[202:203], 0, s[70:71]
	s_mov_b32 m0, s11
	ds_read_b128 v[190:193], v1 offset:49152
	ds_read_b128 v[194:197], v1 offset:50176
	ds_read_b128 v[198:201], v1 offset:51200
	ds_read_b128 v[220:223], v1 offset:52224
	ds_read_b128 v[224:227], v1 offset:53248
	ds_read_b128 v[228:231], v1 offset:54272
	ds_read_b128 v[232:235], v1 offset:55296
	ds_read_b128 v[236:239], v1 offset:56320
	global_load_lds_dwordx4 v[172:173], off
	v_lshl_add_u64 v[172:173], v[240:241], 0, s[70:71]
	s_add_i32 m0, s11, 0x2000
	s_add_i32 s11, s69, s73
	global_load_lds_dwordx4 v[172:173], off
	v_lshl_add_u64 v[172:173], v[244:245], 0, s[70:71]
	s_mov_b32 m0, s11
	s_nop 0
	global_load_lds_dwordx4 v[172:173], off
	v_lshl_add_u64 v[172:173], v[246:247], 0, s[70:71]
	s_add_i32 m0, s11, 0x2000
	s_nop 0
	global_load_lds_dwordx4 v[172:173], off
	v_lshl_add_u64 v[172:173], v[248:249], 0, s[70:71]
	s_mov_b32 m0, s7
	s_nop 0
	global_load_lds_dwordx4 v[172:173], off
	v_lshl_add_u64 v[172:173], v[250:251], 0, s[70:71]
	s_mov_b32 m0, s6
	s_nop 0
	global_load_lds_dwordx4 v[172:173], off
	s_waitcnt vmcnt(8)
	s_waitcnt lgkmcnt(0)
	s_barrier
	s_setprio 1
	s_waitcnt lgkmcnt(0)
	v_mfma_f32_16x16x32_bf16 v[70:73], v[138:141], v[190:193], v[70:73]
	v_mfma_f32_16x16x32_bf16 v[66:69], v[146:149], v[190:193], v[66:69]
	v_mfma_f32_16x16x32_bf16 v[58:61], v[138:141], v[198:201], v[58:61]
	v_mfma_f32_16x16x32_bf16 v[50:53], v[146:149], v[198:201], v[50:53]
	v_mfma_f32_16x16x32_bf16 v[42:45], v[138:141], v[224:227], v[42:45]
	v_mfma_f32_16x16x32_bf16 v[34:37], v[146:149], v[224:227], v[34:37]
	v_mfma_f32_16x16x32_bf16 v[22:25], v[138:141], v[232:235], v[22:25]
	v_mfma_f32_16x16x32_bf16 v[18:21], v[146:149], v[232:235], v[18:21]
	v_mfma_f32_16x16x32_bf16 v[70:73], v[142:145], v[194:197], v[70:73]
	v_mfma_f32_16x16x32_bf16 v[66:69], v[150:153], v[194:197], v[66:69]
	v_mfma_f32_16x16x32_bf16 v[58:61], v[142:145], v[220:223], v[58:61]
	v_mfma_f32_16x16x32_bf16 v[50:53], v[150:153], v[220:223], v[50:53]
	v_mfma_f32_16x16x32_bf16 v[42:45], v[142:145], v[228:231], v[42:45]
	v_mfma_f32_16x16x32_bf16 v[34:37], v[150:153], v[228:231], v[34:37]
	v_mfma_f32_16x16x32_bf16 v[22:25], v[142:145], v[236:239], v[22:25]
	v_mfma_f32_16x16x32_bf16 v[18:21], v[150:153], v[236:239], v[18:21]
	s_setprio 0
	s_setprio 1
	v_mfma_f32_16x16x32_bf16 v[62:65], v[164:167], v[190:193], v[62:65]
	v_mfma_f32_16x16x32_bf16 v[54:57], v[182:185], v[190:193], v[54:57]
	v_mfma_f32_16x16x32_bf16 v[46:49], v[164:167], v[198:201], v[46:49]
	v_mfma_f32_16x16x32_bf16 v[38:41], v[182:185], v[198:201], v[38:41]
	v_mfma_f32_16x16x32_bf16 v[30:33], v[164:167], v[224:227], v[30:33]
	v_mfma_f32_16x16x32_bf16 v[26:29], v[182:185], v[224:227], v[26:29]
	v_mfma_f32_16x16x32_bf16 v[14:17], v[164:167], v[232:235], v[14:17]
	v_mfma_f32_16x16x32_bf16 v[10:13], v[182:185], v[232:235], v[10:13]
	v_mfma_f32_16x16x32_bf16 v[62:65], v[178:181], v[194:197], v[62:65]
	v_mfma_f32_16x16x32_bf16 v[54:57], v[186:189], v[194:197], v[54:57]
	v_mfma_f32_16x16x32_bf16 v[46:49], v[178:181], v[220:223], v[46:49]
	v_mfma_f32_16x16x32_bf16 v[38:41], v[186:189], v[220:223], v[38:41]
	v_mfma_f32_16x16x32_bf16 v[30:33], v[178:181], v[228:231], v[30:33]
	v_mfma_f32_16x16x32_bf16 v[26:29], v[186:189], v[228:231], v[26:29]
	v_mfma_f32_16x16x32_bf16 v[14:17], v[178:181], v[236:239], v[14:17]
	v_mfma_f32_16x16x32_bf16 v[10:13], v[186:189], v[236:239], v[10:13]
	s_setprio 0
	s_add_u32 s0, s0, 0x100
	s_addc_u32 s1, s1, 0
	s_add_u32 s3, s3, 0x100
	s_addc_u32 s10, s10, 0
	s_cmp_ge_u32 s26, s95
	s_mov_b32 s11, s26
	s_cbranch_scc1 .Lrot_exit_328
	s_add_i32 s26, s11, 2
	s_add_u32 s69, s0, 0x80
	s_addc_u32 s74, s1, 0
	s_cmp_eq_u32 s72, s11
	s_cselect_b32 s83, s23, s74
	s_cselect_b32 s82, s22, s69
	v_add_u32_e32 v2, s91, v176
	s_cselect_b32 s75, s25, s10
	s_cselect_b32 s74, s24, s3
	s_add_i32 s11, 0, 0x14000
	s_barrier
	s_branch .LBB0_328
.Lrot_exit_328:
	s_barrier
	s_and_b64 vcc, exec, s[18:19]
	s_cbranch_vccz .LBB0_331
	s_barrier
